# out-GEMM A-operand (H) LDS-DMA loads marked nt so once-read H is evicted before XN (LN re-reads XN); on top of v022
# baseline (speedup 1.0000x reference)
.LBB0_263:
	s_add_u32 s84, s54, 0x100
	s_addc_u32 s85, s55, 0
	s_mov_b32 s86, -2
	ds_read_b128 v[152:155], v149
	ds_read_b128 v[156:159], v149 offset:1024
	ds_read_b128 v[160:163], v149 offset:2048
	ds_read_b128 v[164:167], v149 offset:3072
	ds_read_b128 v[168:171], v150
	ds_read_b128 v[172:175], v150 offset:1024
	ds_read_b128 v[176:179], v150 offset:2048
	ds_read_b128 v[184:187], v150 offset:3072
	s_add_u32 s54, s52, 0x100
	s_addc_u32 s55, s53, 0
	s_cmp_eq_u32 s86, 40
	s_cselect_b32 s59, s7, s55
	s_cselect_b32 s58, s6, s54
	s_cselect_b32 s57, s49, s85
	s_cselect_b32 s56, s48, s84
	v_lshl_add_u64 v[144:145], s[52:53], 0, v[136:137]
	s_add_i32 m0, s63, 0xc000
	ds_read_b128 v[188:191], v151
	ds_read_b128 v[192:195], v151 offset:1024
	ds_read_b128 v[196:199], v151 offset:2048
	ds_read_b128 v[200:203], v151 offset:3072
	ds_read_b128 v[204:207], v151 offset:4096
	ds_read_b128 v[208:211], v151 offset:5120
	ds_read_b128 v[212:215], v151 offset:6144
	ds_read_b128 v[216:219], v151 offset:7168
	global_load_lds_dwordx4 v[144:145], off nt
	v_lshl_add_u64 v[144:145], s[52:53], 0, v[138:139]
	s_add_i32 m0, s63, 0xe000
	s_nop 0
	global_load_lds_dwordx4 v[144:145], off nt
	s_waitcnt vmcnt(8)
	s_waitcnt lgkmcnt(0)
	s_barrier
	s_setprio 1
	s_waitcnt lgkmcnt(0)
	v_mfma_f32_16x16x32_bf16 v[124:127], v[152:155], v[188:191], 0
	v_mfma_f32_16x16x32_bf16 v[124:127], v[156:159], v[192:195], v[124:127]
	v_mfma_f32_16x16x32_bf16 v[120:123], v[160:163], v[188:191], 0
	v_mfma_f32_16x16x32_bf16 v[120:123], v[164:167], v[192:195], v[120:123]
	v_mfma_f32_16x16x32_bf16 v[116:119], v[152:155], v[196:199], 0
	v_mfma_f32_16x16x32_bf16 v[116:119], v[156:159], v[200:203], v[116:119]
	v_mfma_f32_16x16x32_bf16 v[108:111], v[160:163], v[196:199], 0
	v_mfma_f32_16x16x32_bf16 v[108:111], v[164:167], v[200:203], v[108:111]
	v_mfma_f32_16x16x32_bf16 v[100:103], v[152:155], v[204:207], 0
	v_mfma_f32_16x16x32_bf16 v[100:103], v[156:159], v[208:211], v[100:103]
	v_mfma_f32_16x16x32_bf16 v[92:95], v[160:163], v[204:207], 0
	v_mfma_f32_16x16x32_bf16 v[92:95], v[164:167], v[208:211], v[92:95]
	v_mfma_f32_16x16x32_bf16 v[84:87], v[152:155], v[212:215], 0
	v_mfma_f32_16x16x32_bf16 v[84:87], v[156:159], v[216:219], v[84:87]
	v_mfma_f32_16x16x32_bf16 v[76:79], v[160:163], v[212:215], 0
	v_mfma_f32_16x16x32_bf16 v[76:79], v[164:167], v[216:219], v[76:79]
	v_mfma_f32_16x16x32_bf16 v[112:115], v[168:171], v[188:191], 0
	v_mfma_f32_16x16x32_bf16 v[112:115], v[172:175], v[192:195], v[112:115]
	v_mfma_f32_16x16x32_bf16 v[104:107], v[176:179], v[188:191], 0
	v_mfma_f32_16x16x32_bf16 v[104:107], v[184:187], v[192:195], v[104:107]
	v_mfma_f32_16x16x32_bf16 v[96:99], v[168:171], v[196:199], 0
	v_mfma_f32_16x16x32_bf16 v[96:99], v[172:175], v[200:203], v[96:99]
	v_mfma_f32_16x16x32_bf16 v[88:91], v[176:179], v[196:199], 0
	v_mfma_f32_16x16x32_bf16 v[88:91], v[184:187], v[200:203], v[88:91]
	v_mfma_f32_16x16x32_bf16 v[80:83], v[168:171], v[204:207], 0
	v_mfma_f32_16x16x32_bf16 v[80:83], v[172:175], v[208:211], v[80:83]
	v_mfma_f32_16x16x32_bf16 v[72:75], v[176:179], v[204:207], 0
	v_mfma_f32_16x16x32_bf16 v[72:75], v[184:187], v[208:211], v[72:75]
	v_mfma_f32_16x16x32_bf16 v[68:71], v[168:171], v[212:215], 0
	v_mfma_f32_16x16x32_bf16 v[68:71], v[172:175], v[216:219], v[68:71]
	v_mfma_f32_16x16x32_bf16 v[64:67], v[176:179], v[212:215], 0
	v_mfma_f32_16x16x32_bf16 v[64:67], v[184:187], v[216:219], v[64:67]
	s_setprio 0
	s_barrier
	s_add_i32 s18, s70, s62
	v_lshl_add_u64 v[144:145], s[56:57], 0, v[130:131]
	s_mov_b32 m0, s18
	ds_read_b128 v[188:191], v151 offset:16384
	ds_read_b128 v[192:195], v151 offset:17408
	ds_read_b128 v[196:199], v151 offset:18432
	ds_read_b128 v[200:203], v151 offset:19456
	ds_read_b128 v[204:207], v151 offset:20480
	ds_read_b128 v[208:211], v151 offset:21504
	ds_read_b128 v[212:215], v151 offset:22528
	ds_read_b128 v[216:219], v151 offset:23552
	global_load_lds_dwordx4 v[144:145], off
	s_add_i32 m0, s18, 0x2000
	s_add_u32 s52, s56, 0xb0000
	v_lshl_add_u64 v[220:221], s[56:57], 0, v[134:135]
	s_addc_u32 s53, s57, 0
	s_add_i32 s18, s71, s62
	global_load_lds_dwordx4 v[220:221], off
	v_lshl_add_u64 v[222:223], s[52:53], 0, v[130:131]
	s_mov_b32 m0, s18
	v_lshl_add_u64 v[224:225], s[58:59], 0, v[132:133]
	global_load_lds_dwordx4 v[222:223], off
	v_lshl_add_u64 v[222:223], s[52:53], 0, v[134:135]
	s_add_i32 m0, s18, 0x2000
	s_nop 0
	global_load_lds_dwordx4 v[222:223], off
	v_lshl_add_u64 v[222:223], s[58:59], 0, v[128:129]
	s_mov_b32 m0, s63
	s_nop 0
	global_load_lds_dwordx4 v[222:223], off nt
	s_mov_b32 m0, s64
	s_nop 0
	global_load_lds_dwordx4 v[224:225], off nt
	s_waitcnt vmcnt(8)
	s_waitcnt lgkmcnt(0)
	s_barrier
	s_setprio 1
	s_waitcnt lgkmcnt(0)
	v_mfma_f32_16x16x32_bf16 v[60:63], v[152:155], v[188:191], 0
	v_mfma_f32_16x16x32_bf16 v[60:63], v[156:159], v[192:195], v[60:63]
	v_mfma_f32_16x16x32_bf16 v[56:59], v[160:163], v[188:191], 0
	v_mfma_f32_16x16x32_bf16 v[56:59], v[164:167], v[192:195], v[56:59]
	v_mfma_f32_16x16x32_bf16 v[52:55], v[152:155], v[196:199], 0
	v_mfma_f32_16x16x32_bf16 v[52:55], v[156:159], v[200:203], v[52:55]
	v_mfma_f32_16x16x32_bf16 v[44:47], v[160:163], v[196:199], 0
	v_mfma_f32_16x16x32_bf16 v[44:47], v[164:167], v[200:203], v[44:47]
	v_mfma_f32_16x16x32_bf16 v[36:39], v[152:155], v[204:207], 0
	v_mfma_f32_16x16x32_bf16 v[36:39], v[156:159], v[208:211], v[36:39]
	v_mfma_f32_16x16x32_bf16 v[28:31], v[160:163], v[204:207], 0
	v_mfma_f32_16x16x32_bf16 v[28:31], v[164:167], v[208:211], v[28:31]
	v_mfma_f32_16x16x32_bf16 v[20:23], v[152:155], v[212:215], 0
	v_mfma_f32_16x16x32_bf16 v[20:23], v[156:159], v[216:219], v[20:23]
	v_mfma_f32_16x16x32_bf16 v[12:15], v[160:163], v[212:215], 0
	v_mfma_f32_16x16x32_bf16 v[12:15], v[164:167], v[216:219], v[12:15]
	v_mfma_f32_16x16x32_bf16 v[48:51], v[168:171], v[188:191], 0
	v_mfma_f32_16x16x32_bf16 v[48:51], v[172:175], v[192:195], v[48:51]
	v_mfma_f32_16x16x32_bf16 v[40:43], v[176:179], v[188:191], 0
	v_mfma_f32_16x16x32_bf16 v[40:43], v[184:187], v[192:195], v[40:43]
	v_mfma_f32_16x16x32_bf16 v[32:35], v[168:171], v[196:199], 0
	v_mfma_f32_16x16x32_bf16 v[32:35], v[172:175], v[200:203], v[32:35]
	v_mfma_f32_16x16x32_bf16 v[24:27], v[176:179], v[196:199], 0
	v_mfma_f32_16x16x32_bf16 v[24:27], v[184:187], v[200:203], v[24:27]
	v_mfma_f32_16x16x32_bf16 v[16:19], v[168:171], v[204:207], 0
	v_mfma_f32_16x16x32_bf16 v[16:19], v[172:175], v[208:211], v[16:19]
	v_mfma_f32_16x16x32_bf16 v[8:11], v[176:179], v[204:207], 0
	v_mfma_f32_16x16x32_bf16 v[8:11], v[184:187], v[208:211], v[8:11]
	v_mfma_f32_16x16x32_bf16 v[4:7], v[168:171], v[212:215], 0
	v_mfma_f32_16x16x32_bf16 v[4:7], v[172:175], v[216:219], v[4:7]
	v_mfma_f32_16x16x32_bf16 v[0:3], v[176:179], v[212:215], 0
	v_mfma_f32_16x16x32_bf16 v[0:3], v[184:187], v[216:219], v[0:3]
	s_setprio 0
	s_barrier
	s_branch .Lmid_gemm1
.LBB0_264:
	ds_read_b128 v[152:155], v149
	ds_read_b128 v[156:159], v149 offset:1024
	ds_read_b128 v[160:163], v149 offset:2048
	ds_read_b128 v[164:167], v149 offset:3072
	ds_read_b128 v[168:171], v150
	ds_read_b128 v[172:175], v150 offset:1024
	ds_read_b128 v[176:179], v150 offset:2048
	ds_read_b128 v[184:187], v150 offset:3072
	s_add_u32 s54, s52, 0x100
	s_addc_u32 s55, s53, 0
	s_cmp_eq_u32 s86, 40
	s_cselect_b32 s59, s7, s55
	s_cselect_b32 s58, s6, s54
	s_cselect_b32 s57, s49, s85
	s_cselect_b32 s56, s48, s84
	v_lshl_add_u64 v[144:145], s[52:53], 0, v[136:137]
	s_add_i32 m0, s63, 0xc000
	ds_read_b128 v[188:191], v151
	ds_read_b128 v[192:195], v151 offset:1024
	ds_read_b128 v[196:199], v151 offset:2048
	ds_read_b128 v[200:203], v151 offset:3072
	ds_read_b128 v[204:207], v151 offset:4096
	ds_read_b128 v[208:211], v151 offset:5120
	ds_read_b128 v[212:215], v151 offset:6144
	ds_read_b128 v[216:219], v151 offset:7168
	global_load_lds_dwordx4 v[144:145], off nt
	v_lshl_add_u64 v[144:145], s[52:53], 0, v[138:139]
	s_add_i32 m0, s63, 0xe000
	s_nop 0
	global_load_lds_dwordx4 v[144:145], off nt
	s_waitcnt vmcnt(8)
	s_waitcnt lgkmcnt(0)
	s_barrier
	s_setprio 1
	s_waitcnt lgkmcnt(0)
	v_mfma_f32_16x16x32_bf16 v[124:127], v[152:155], v[188:191], v[124:127]
	v_mfma_f32_16x16x32_bf16 v[124:127], v[156:159], v[192:195], v[124:127]
	v_mfma_f32_16x16x32_bf16 v[120:123], v[160:163], v[188:191], v[120:123]
	v_mfma_f32_16x16x32_bf16 v[120:123], v[164:167], v[192:195], v[120:123]
	v_mfma_f32_16x16x32_bf16 v[116:119], v[152:155], v[196:199], v[116:119]
	v_mfma_f32_16x16x32_bf16 v[116:119], v[156:159], v[200:203], v[116:119]
	v_mfma_f32_16x16x32_bf16 v[108:111], v[160:163], v[196:199], v[108:111]
	v_mfma_f32_16x16x32_bf16 v[108:111], v[164:167], v[200:203], v[108:111]
	v_mfma_f32_16x16x32_bf16 v[100:103], v[152:155], v[204:207], v[100:103]
	v_mfma_f32_16x16x32_bf16 v[100:103], v[156:159], v[208:211], v[100:103]
	v_mfma_f32_16x16x32_bf16 v[92:95], v[160:163], v[204:207], v[92:95]
	v_mfma_f32_16x16x32_bf16 v[92:95], v[164:167], v[208:211], v[92:95]
	v_mfma_f32_16x16x32_bf16 v[84:87], v[152:155], v[212:215], v[84:87]
	v_mfma_f32_16x16x32_bf16 v[84:87], v[156:159], v[216:219], v[84:87]
	v_mfma_f32_16x16x32_bf16 v[76:79], v[160:163], v[212:215], v[76:79]
	v_mfma_f32_16x16x32_bf16 v[76:79], v[164:167], v[216:219], v[76:79]
	v_mfma_f32_16x16x32_bf16 v[112:115], v[168:171], v[188:191], v[112:115]
	v_mfma_f32_16x16x32_bf16 v[112:115], v[172:175], v[192:195], v[112:115]
	v_mfma_f32_16x16x32_bf16 v[104:107], v[176:179], v[188:191], v[104:107]
	v_mfma_f32_16x16x32_bf16 v[104:107], v[184:187], v[192:195], v[104:107]
	v_mfma_f32_16x16x32_bf16 v[96:99], v[168:171], v[196:199], v[96:99]
	v_mfma_f32_16x16x32_bf16 v[96:99], v[172:175], v[200:203], v[96:99]
	v_mfma_f32_16x16x32_bf16 v[88:91], v[176:179], v[196:199], v[88:91]
	v_mfma_f32_16x16x32_bf16 v[88:91], v[184:187], v[200:203], v[88:91]
	v_mfma_f32_16x16x32_bf16 v[80:83], v[168:171], v[204:207], v[80:83]
	v_mfma_f32_16x16x32_bf16 v[80:83], v[172:175], v[208:211], v[80:83]
	v_mfma_f32_16x16x32_bf16 v[72:75], v[176:179], v[204:207], v[72:75]
	v_mfma_f32_16x16x32_bf16 v[72:75], v[184:187], v[208:211], v[72:75]
	v_mfma_f32_16x16x32_bf16 v[68:71], v[168:171], v[212:215], v[68:71]
	v_mfma_f32_16x16x32_bf16 v[68:71], v[172:175], v[216:219], v[68:71]
	v_mfma_f32_16x16x32_bf16 v[64:67], v[176:179], v[212:215], v[64:67]
	v_mfma_f32_16x16x32_bf16 v[64:67], v[184:187], v[216:219], v[64:67]
	s_setprio 0
	s_barrier
	s_add_i32 s18, s70, s62
	v_lshl_add_u64 v[144:145], s[56:57], 0, v[130:131]
	s_mov_b32 m0, s18
	ds_read_b128 v[188:191], v151 offset:16384
	ds_read_b128 v[192:195], v151 offset:17408
	ds_read_b128 v[196:199], v151 offset:18432
	ds_read_b128 v[200:203], v151 offset:19456
	ds_read_b128 v[204:207], v151 offset:20480
	ds_read_b128 v[208:211], v151 offset:21504
	ds_read_b128 v[212:215], v151 offset:22528
	ds_read_b128 v[216:219], v151 offset:23552
	global_load_lds_dwordx4 v[144:145], off
	s_add_i32 m0, s18, 0x2000
	s_add_u32 s52, s56, 0xb0000
	v_lshl_add_u64 v[220:221], s[56:57], 0, v[134:135]
	s_addc_u32 s53, s57, 0
	s_add_i32 s18, s71, s62
	global_load_lds_dwordx4 v[220:221], off
	v_lshl_add_u64 v[222:223], s[52:53], 0, v[130:131]
	s_mov_b32 m0, s18
	v_lshl_add_u64 v[224:225], s[58:59], 0, v[132:133]
	global_load_lds_dwordx4 v[222:223], off
	v_lshl_add_u64 v[222:223], s[52:53], 0, v[134:135]
	s_add_i32 m0, s18, 0x2000
	s_nop 0
	global_load_lds_dwordx4 v[222:223], off
	v_lshl_add_u64 v[222:223], s[58:59], 0, v[128:129]
	s_mov_b32 m0, s63
	s_nop 0
	global_load_lds_dwordx4 v[222:223], off nt
	s_mov_b32 m0, s64
	s_nop 0
	global_load_lds_dwordx4 v[224:225], off nt
	s_waitcnt vmcnt(8)
	s_waitcnt lgkmcnt(0)
	s_barrier
	s_setprio 1
	s_waitcnt lgkmcnt(0)
	v_mfma_f32_16x16x32_bf16 v[60:63], v[152:155], v[188:191], v[60:63]
	v_mfma_f32_16x16x32_bf16 v[60:63], v[156:159], v[192:195], v[60:63]
	v_mfma_f32_16x16x32_bf16 v[56:59], v[160:163], v[188:191], v[56:59]
	v_mfma_f32_16x16x32_bf16 v[56:59], v[164:167], v[192:195], v[56:59]
	v_mfma_f32_16x16x32_bf16 v[52:55], v[152:155], v[196:199], v[52:55]
	v_mfma_f32_16x16x32_bf16 v[52:55], v[156:159], v[200:203], v[52:55]
	v_mfma_f32_16x16x32_bf16 v[44:47], v[160:163], v[196:199], v[44:47]
	v_mfma_f32_16x16x32_bf16 v[44:47], v[164:167], v[200:203], v[44:47]
	v_mfma_f32_16x16x32_bf16 v[36:39], v[152:155], v[204:207], v[36:39]
	v_mfma_f32_16x16x32_bf16 v[36:39], v[156:159], v[208:211], v[36:39]
	v_mfma_f32_16x16x32_bf16 v[28:31], v[160:163], v[204:207], v[28:31]
	v_mfma_f32_16x16x32_bf16 v[28:31], v[164:167], v[208:211], v[28:31]
	v_mfma_f32_16x16x32_bf16 v[20:23], v[152:155], v[212:215], v[20:23]
	v_mfma_f32_16x16x32_bf16 v[20:23], v[156:159], v[216:219], v[20:23]
	v_mfma_f32_16x16x32_bf16 v[12:15], v[160:163], v[212:215], v[12:15]
	v_mfma_f32_16x16x32_bf16 v[12:15], v[164:167], v[216:219], v[12:15]
	v_mfma_f32_16x16x32_bf16 v[48:51], v[168:171], v[188:191], v[48:51]
	v_mfma_f32_16x16x32_bf16 v[48:51], v[172:175], v[192:195], v[48:51]
	v_mfma_f32_16x16x32_bf16 v[40:43], v[176:179], v[188:191], v[40:43]
	v_mfma_f32_16x16x32_bf16 v[40:43], v[184:187], v[192:195], v[40:43]
	v_mfma_f32_16x16x32_bf16 v[32:35], v[168:171], v[196:199], v[32:35]
	v_mfma_f32_16x16x32_bf16 v[32:35], v[172:175], v[200:203], v[32:35]
	v_mfma_f32_16x16x32_bf16 v[24:27], v[176:179], v[196:199], v[24:27]
	v_mfma_f32_16x16x32_bf16 v[24:27], v[184:187], v[200:203], v[24:27]
	v_mfma_f32_16x16x32_bf16 v[16:19], v[168:171], v[204:207], v[16:19]
	v_mfma_f32_16x16x32_bf16 v[16:19], v[172:175], v[208:211], v[16:19]
	v_mfma_f32_16x16x32_bf16 v[8:11], v[176:179], v[204:207], v[8:11]
	v_mfma_f32_16x16x32_bf16 v[8:11], v[184:187], v[208:211], v[8:11]
	v_mfma_f32_16x16x32_bf16 v[4:7], v[168:171], v[212:215], v[4:7]
	v_mfma_f32_16x16x32_bf16 v[4:7], v[172:175], v[216:219], v[4:7]
	v_mfma_f32_16x16x32_bf16 v[0:3], v[176:179], v[212:215], v[0:3]
	v_mfma_f32_16x16x32_bf16 v[0:3], v[184:187], v[216:219], v[0:3]
	s_setprio 0
	s_barrier
.Lmid_gemm1:
	s_add_i32 s18, 0, 0x18000
	s_add_i32 s19, 0, 0x1c000
	v_add_u32_e32 v164, s18, v147
	v_add_u32_e32 v181, s19, v147
	ds_read_b128 v[152:155], v164
	ds_read_b128 v[156:159], v164 offset:1024
	ds_read_b128 v[160:163], v164 offset:2048
	ds_read_b128 v[164:167], v164 offset:3072
	ds_read_b128 v[168:171], v181
	ds_read_b128 v[172:175], v181 offset:1024
	ds_read_b128 v[176:179], v181 offset:2048
	ds_read_b128 v[184:187], v181 offset:3072
	s_add_u32 s52, s58, 0xb0000
	s_addc_u32 s53, s59, 0
	s_mov_b32 m0, s65
	v_lshl_add_u64 v[226:227], s[52:53], 0, v[128:129]
	ds_read_b128 v[188:191], v151 offset:32768
	ds_read_b128 v[192:195], v151 offset:33792
	ds_read_b128 v[196:199], v151 offset:34816
	ds_read_b128 v[200:203], v151 offset:35840
	ds_read_b128 v[204:207], v151 offset:36864
	ds_read_b128 v[208:211], v151 offset:37888
	ds_read_b128 v[212:215], v151 offset:38912
	ds_read_b128 v[216:219], v151 offset:39936
	global_load_lds_dwordx4 v[226:227], off nt
	v_lshl_add_u64 v[226:227], s[52:53], 0, v[132:133]
	s_mov_b32 m0, s66
	s_nop 0
	global_load_lds_dwordx4 v[226:227], off nt
	s_waitcnt vmcnt(8)
	s_waitcnt lgkmcnt(0)
	s_barrier
	s_setprio 1
	s_waitcnt lgkmcnt(0)
	v_mfma_f32_16x16x32_bf16 v[124:127], v[152:155], v[188:191], v[124:127]
	v_mfma_f32_16x16x32_bf16 v[124:127], v[156:159], v[192:195], v[124:127]
	v_mfma_f32_16x16x32_bf16 v[120:123], v[160:163], v[188:191], v[120:123]
	v_mfma_f32_16x16x32_bf16 v[120:123], v[164:167], v[192:195], v[120:123]
	v_mfma_f32_16x16x32_bf16 v[116:119], v[152:155], v[196:199], v[116:119]
	v_mfma_f32_16x16x32_bf16 v[116:119], v[156:159], v[200:203], v[116:119]
	v_mfma_f32_16x16x32_bf16 v[108:111], v[160:163], v[196:199], v[108:111]
	v_mfma_f32_16x16x32_bf16 v[108:111], v[164:167], v[200:203], v[108:111]
	v_mfma_f32_16x16x32_bf16 v[100:103], v[152:155], v[204:207], v[100:103]
	v_mfma_f32_16x16x32_bf16 v[100:103], v[156:159], v[208:211], v[100:103]
	v_mfma_f32_16x16x32_bf16 v[92:95], v[160:163], v[204:207], v[92:95]
	v_mfma_f32_16x16x32_bf16 v[92:95], v[164:167], v[208:211], v[92:95]
	v_mfma_f32_16x16x32_bf16 v[84:87], v[152:155], v[212:215], v[84:87]
	v_mfma_f32_16x16x32_bf16 v[84:87], v[156:159], v[216:219], v[84:87]
	v_mfma_f32_16x16x32_bf16 v[76:79], v[160:163], v[212:215], v[76:79]
	v_mfma_f32_16x16x32_bf16 v[76:79], v[164:167], v[216:219], v[76:79]
	v_mfma_f32_16x16x32_bf16 v[112:115], v[168:171], v[188:191], v[112:115]
	v_mfma_f32_16x16x32_bf16 v[112:115], v[172:175], v[192:195], v[112:115]
	v_mfma_f32_16x16x32_bf16 v[104:107], v[176:179], v[188:191], v[104:107]
	v_mfma_f32_16x16x32_bf16 v[104:107], v[184:187], v[192:195], v[104:107]
	v_mfma_f32_16x16x32_bf16 v[96:99], v[168:171], v[196:199], v[96:99]
	v_mfma_f32_16x16x32_bf16 v[96:99], v[172:175], v[200:203], v[96:99]
	v_mfma_f32_16x16x32_bf16 v[88:91], v[176:179], v[196:199], v[88:91]
	v_mfma_f32_16x16x32_bf16 v[88:91], v[184:187], v[200:203], v[88:91]
	v_mfma_f32_16x16x32_bf16 v[80:83], v[168:171], v[204:207], v[80:83]
	v_mfma_f32_16x16x32_bf16 v[80:83], v[172:175], v[208:211], v[80:83]
	v_mfma_f32_16x16x32_bf16 v[72:75], v[176:179], v[204:207], v[72:75]
	v_mfma_f32_16x16x32_bf16 v[72:75], v[184:187], v[208:211], v[72:75]
	v_mfma_f32_16x16x32_bf16 v[68:71], v[168:171], v[212:215], v[68:71]
	v_mfma_f32_16x16x32_bf16 v[68:71], v[172:175], v[216:219], v[68:71]
	v_mfma_f32_16x16x32_bf16 v[64:67], v[176:179], v[212:215], v[64:67]
	v_mfma_f32_16x16x32_bf16 v[64:67], v[184:187], v[216:219], v[64:67]
	s_setprio 0
	s_barrier
	s_add_i32 s18, s18, s62
	v_lshl_add_u64 v[144:145], v[144:145], 0, s[8:9]
	s_mov_b32 m0, s18
	ds_read_b128 v[188:191], v151 offset:49152
	ds_read_b128 v[192:195], v151 offset:50176
	ds_read_b128 v[196:199], v151 offset:51200
	ds_read_b128 v[200:203], v151 offset:52224
	ds_read_b128 v[204:207], v151 offset:53248
	ds_read_b128 v[208:211], v151 offset:54272
	ds_read_b128 v[212:215], v151 offset:55296
	ds_read_b128 v[216:219], v151 offset:56320
	global_load_lds_dwordx4 v[144:145], off
	s_add_i32 m0, s18, 0x2000
	s_add_u32 s52, s56, 0xb0080
	v_lshl_add_u64 v[144:145], v[220:221], 0, s[8:9]
	s_addc_u32 s53, s57, 0
	s_add_i32 s18, s19, s62
	global_load_lds_dwordx4 v[144:145], off
	v_lshl_add_u64 v[144:145], s[52:53], 0, v[130:131]
	s_mov_b32 m0, s18
	s_nop 0
	global_load_lds_dwordx4 v[144:145], off
	v_lshl_add_u64 v[144:145], s[52:53], 0, v[134:135]
	s_add_i32 m0, s18, 0x2000
	s_nop 0
	global_load_lds_dwordx4 v[144:145], off
	v_lshl_add_u64 v[144:145], v[222:223], 0, s[8:9]
	s_mov_b32 m0, s68
	s_nop 0
	global_load_lds_dwordx4 v[144:145], off nt
	v_lshl_add_u64 v[144:145], v[224:225], 0, s[8:9]
	s_mov_b32 m0, s69
	s_nop 0
	global_load_lds_dwordx4 v[144:145], off nt
	s_waitcnt vmcnt(8)
	s_waitcnt lgkmcnt(0)
	s_barrier
	s_setprio 1
	s_waitcnt lgkmcnt(0)
	v_mfma_f32_16x16x32_bf16 v[60:63], v[152:155], v[188:191], v[60:63]
	v_mfma_f32_16x16x32_bf16 v[60:63], v[156:159], v[192:195], v[60:63]
	v_mfma_f32_16x16x32_bf16 v[56:59], v[160:163], v[188:191], v[56:59]
	v_mfma_f32_16x16x32_bf16 v[56:59], v[164:167], v[192:195], v[56:59]
	v_mfma_f32_16x16x32_bf16 v[52:55], v[152:155], v[196:199], v[52:55]
	v_mfma_f32_16x16x32_bf16 v[52:55], v[156:159], v[200:203], v[52:55]
	v_mfma_f32_16x16x32_bf16 v[44:47], v[160:163], v[196:199], v[44:47]
	v_mfma_f32_16x16x32_bf16 v[44:47], v[164:167], v[200:203], v[44:47]
	v_mfma_f32_16x16x32_bf16 v[36:39], v[152:155], v[204:207], v[36:39]
	v_mfma_f32_16x16x32_bf16 v[36:39], v[156:159], v[208:211], v[36:39]
	v_mfma_f32_16x16x32_bf16 v[28:31], v[160:163], v[204:207], v[28:31]
	v_mfma_f32_16x16x32_bf16 v[28:31], v[164:167], v[208:211], v[28:31]
	v_mfma_f32_16x16x32_bf16 v[20:23], v[152:155], v[212:215], v[20:23]
	v_mfma_f32_16x16x32_bf16 v[20:23], v[156:159], v[216:219], v[20:23]
	v_mfma_f32_16x16x32_bf16 v[12:15], v[160:163], v[212:215], v[12:15]
	v_mfma_f32_16x16x32_bf16 v[12:15], v[164:167], v[216:219], v[12:15]
	v_mfma_f32_16x16x32_bf16 v[48:51], v[168:171], v[188:191], v[48:51]
	v_mfma_f32_16x16x32_bf16 v[48:51], v[172:175], v[192:195], v[48:51]
	v_mfma_f32_16x16x32_bf16 v[40:43], v[176:179], v[188:191], v[40:43]
	v_mfma_f32_16x16x32_bf16 v[40:43], v[184:187], v[192:195], v[40:43]
	v_mfma_f32_16x16x32_bf16 v[32:35], v[168:171], v[196:199], v[32:35]
	v_mfma_f32_16x16x32_bf16 v[32:35], v[172:175], v[200:203], v[32:35]
	v_mfma_f32_16x16x32_bf16 v[24:27], v[176:179], v[196:199], v[24:27]
	v_mfma_f32_16x16x32_bf16 v[24:27], v[184:187], v[200:203], v[24:27]
	v_mfma_f32_16x16x32_bf16 v[16:19], v[168:171], v[204:207], v[16:19]
	v_mfma_f32_16x16x32_bf16 v[16:19], v[172:175], v[208:211], v[16:19]
	v_mfma_f32_16x16x32_bf16 v[8:11], v[176:179], v[204:207], v[8:11]
	v_mfma_f32_16x16x32_bf16 v[8:11], v[184:187], v[208:211], v[8:11]
	v_mfma_f32_16x16x32_bf16 v[4:7], v[168:171], v[212:215], v[4:7]
	v_mfma_f32_16x16x32_bf16 v[4:7], v[172:175], v[216:219], v[4:7]
	v_mfma_f32_16x16x32_bf16 v[0:3], v[176:179], v[212:215], v[0:3]
	v_mfma_f32_16x16x32_bf16 v[0:3], v[184:187], v[216:219], v[0:3]
	s_setprio 0
	s_barrier
	s_add_i32 s86, s86, 2
	s_add_u32 s84, s84, 0x100
	s_addc_u32 s85, s85, 0
	s_cmp_gt_u32 s86, 41
	s_mov_b64 s[52:53], s[54:55]
	s_cbranch_scc0 .LBB0_264
	s_and_b64 vcc, exec, s[10:11]
	s_cbranch_vccz .LBB0_267
	s_barrier

.LBB0_803:
	s_add_u32 s84, s54, 0x100
	s_addc_u32 s85, s55, 0
	s_mov_b32 s86, -2
	ds_read_b128 v[152:155], v149
	ds_read_b128 v[156:159], v149 offset:1024
	ds_read_b128 v[160:163], v149 offset:2048
	ds_read_b128 v[164:167], v149 offset:3072
	ds_read_b128 v[168:171], v150
	ds_read_b128 v[172:175], v150 offset:1024
	ds_read_b128 v[176:179], v150 offset:2048
	ds_read_b128 v[184:187], v150 offset:3072
	s_add_u32 s54, s52, 0x100
	s_addc_u32 s55, s53, 0
	s_cmp_eq_u32 s86, 40
	s_cselect_b32 s59, s13, s55
	s_cselect_b32 s58, s12, s54
	s_cselect_b32 s57, s49, s85
	s_cselect_b32 s56, s48, s84
	v_lshl_add_u64 v[144:145], s[52:53], 0, v[136:137]
	s_add_i32 m0, s63, 0xc000
	ds_read_b128 v[188:191], v151
	ds_read_b128 v[192:195], v151 offset:1024
	ds_read_b128 v[196:199], v151 offset:2048
	ds_read_b128 v[200:203], v151 offset:3072
	ds_read_b128 v[204:207], v151 offset:4096
	ds_read_b128 v[208:211], v151 offset:5120
	ds_read_b128 v[212:215], v151 offset:6144
	ds_read_b128 v[216:219], v151 offset:7168
	global_load_lds_dwordx4 v[144:145], off nt
	v_lshl_add_u64 v[144:145], s[52:53], 0, v[138:139]
	s_add_i32 m0, s63, 0xe000
	s_nop 0
	global_load_lds_dwordx4 v[144:145], off nt
	s_waitcnt vmcnt(8)
	s_waitcnt lgkmcnt(0)
	s_barrier
	s_setprio 1
	s_waitcnt lgkmcnt(0)
	v_mfma_f32_16x16x32_bf16 v[124:127], v[152:155], v[188:191], 0
	v_mfma_f32_16x16x32_bf16 v[124:127], v[156:159], v[192:195], v[124:127]
	v_mfma_f32_16x16x32_bf16 v[120:123], v[160:163], v[188:191], 0
	v_mfma_f32_16x16x32_bf16 v[120:123], v[164:167], v[192:195], v[120:123]
	v_mfma_f32_16x16x32_bf16 v[116:119], v[152:155], v[196:199], 0
	v_mfma_f32_16x16x32_bf16 v[116:119], v[156:159], v[200:203], v[116:119]
	v_mfma_f32_16x16x32_bf16 v[108:111], v[160:163], v[196:199], 0
	v_mfma_f32_16x16x32_bf16 v[108:111], v[164:167], v[200:203], v[108:111]
	v_mfma_f32_16x16x32_bf16 v[100:103], v[152:155], v[204:207], 0
	v_mfma_f32_16x16x32_bf16 v[100:103], v[156:159], v[208:211], v[100:103]
	v_mfma_f32_16x16x32_bf16 v[92:95], v[160:163], v[204:207], 0
	v_mfma_f32_16x16x32_bf16 v[92:95], v[164:167], v[208:211], v[92:95]
	v_mfma_f32_16x16x32_bf16 v[84:87], v[152:155], v[212:215], 0
	v_mfma_f32_16x16x32_bf16 v[84:87], v[156:159], v[216:219], v[84:87]
	v_mfma_f32_16x16x32_bf16 v[76:79], v[160:163], v[212:215], 0
	v_mfma_f32_16x16x32_bf16 v[76:79], v[164:167], v[216:219], v[76:79]
	v_mfma_f32_16x16x32_bf16 v[112:115], v[168:171], v[188:191], 0
	v_mfma_f32_16x16x32_bf16 v[112:115], v[172:175], v[192:195], v[112:115]
	v_mfma_f32_16x16x32_bf16 v[104:107], v[176:179], v[188:191], 0
	v_mfma_f32_16x16x32_bf16 v[104:107], v[184:187], v[192:195], v[104:107]
	v_mfma_f32_16x16x32_bf16 v[96:99], v[168:171], v[196:199], 0
	v_mfma_f32_16x16x32_bf16 v[96:99], v[172:175], v[200:203], v[96:99]
	v_mfma_f32_16x16x32_bf16 v[88:91], v[176:179], v[196:199], 0
	v_mfma_f32_16x16x32_bf16 v[88:91], v[184:187], v[200:203], v[88:91]
	v_mfma_f32_16x16x32_bf16 v[80:83], v[168:171], v[204:207], 0
	v_mfma_f32_16x16x32_bf16 v[80:83], v[172:175], v[208:211], v[80:83]
	v_mfma_f32_16x16x32_bf16 v[72:75], v[176:179], v[204:207], 0
	v_mfma_f32_16x16x32_bf16 v[72:75], v[184:187], v[208:211], v[72:75]
	v_mfma_f32_16x16x32_bf16 v[68:71], v[168:171], v[212:215], 0
	v_mfma_f32_16x16x32_bf16 v[68:71], v[172:175], v[216:219], v[68:71]
	v_mfma_f32_16x16x32_bf16 v[64:67], v[176:179], v[212:215], 0
	v_mfma_f32_16x16x32_bf16 v[64:67], v[184:187], v[216:219], v[64:67]
	s_setprio 0
	s_barrier
	s_add_i32 s52, s70, s62
	v_lshl_add_u64 v[144:145], s[56:57], 0, v[130:131]
	s_mov_b32 m0, s52
	ds_read_b128 v[188:191], v151 offset:16384
	ds_read_b128 v[192:195], v151 offset:17408
	ds_read_b128 v[196:199], v151 offset:18432
	ds_read_b128 v[200:203], v151 offset:19456
	ds_read_b128 v[204:207], v151 offset:20480
	ds_read_b128 v[208:211], v151 offset:21504
	ds_read_b128 v[212:215], v151 offset:22528
	ds_read_b128 v[216:219], v151 offset:23552
	global_load_lds_dwordx4 v[144:145], off
	s_add_i32 m0, s52, 0x2000
	s_add_u32 s52, s56, 0xb0000
	v_lshl_add_u64 v[220:221], s[56:57], 0, v[134:135]
	s_addc_u32 s53, s57, 0
	s_add_i32 s79, s71, s62
	global_load_lds_dwordx4 v[220:221], off
	v_lshl_add_u64 v[222:223], s[52:53], 0, v[130:131]
	s_mov_b32 m0, s79
	v_lshl_add_u64 v[224:225], s[58:59], 0, v[132:133]
	global_load_lds_dwordx4 v[222:223], off
	v_lshl_add_u64 v[222:223], s[52:53], 0, v[134:135]
	s_add_i32 m0, s79, 0x2000
	s_nop 0
	global_load_lds_dwordx4 v[222:223], off
	v_lshl_add_u64 v[222:223], s[58:59], 0, v[128:129]
	s_mov_b32 m0, s63
	s_nop 0
	global_load_lds_dwordx4 v[222:223], off nt
	s_mov_b32 m0, s64
	s_nop 0
	global_load_lds_dwordx4 v[224:225], off nt
	s_waitcnt vmcnt(8)
	s_waitcnt lgkmcnt(0)
	s_barrier
	s_setprio 1
	s_waitcnt lgkmcnt(0)
	v_mfma_f32_16x16x32_bf16 v[60:63], v[152:155], v[188:191], 0
	v_mfma_f32_16x16x32_bf16 v[60:63], v[156:159], v[192:195], v[60:63]
	v_mfma_f32_16x16x32_bf16 v[56:59], v[160:163], v[188:191], 0
	v_mfma_f32_16x16x32_bf16 v[56:59], v[164:167], v[192:195], v[56:59]
	v_mfma_f32_16x16x32_bf16 v[52:55], v[152:155], v[196:199], 0
	v_mfma_f32_16x16x32_bf16 v[52:55], v[156:159], v[200:203], v[52:55]
	v_mfma_f32_16x16x32_bf16 v[44:47], v[160:163], v[196:199], 0
	v_mfma_f32_16x16x32_bf16 v[44:47], v[164:167], v[200:203], v[44:47]
	v_mfma_f32_16x16x32_bf16 v[36:39], v[152:155], v[204:207], 0
	v_mfma_f32_16x16x32_bf16 v[36:39], v[156:159], v[208:211], v[36:39]
	v_mfma_f32_16x16x32_bf16 v[28:31], v[160:163], v[204:207], 0
	v_mfma_f32_16x16x32_bf16 v[28:31], v[164:167], v[208:211], v[28:31]
	v_mfma_f32_16x16x32_bf16 v[20:23], v[152:155], v[212:215], 0
	v_mfma_f32_16x16x32_bf16 v[20:23], v[156:159], v[216:219], v[20:23]
	v_mfma_f32_16x16x32_bf16 v[12:15], v[160:163], v[212:215], 0
	v_mfma_f32_16x16x32_bf16 v[12:15], v[164:167], v[216:219], v[12:15]
	v_mfma_f32_16x16x32_bf16 v[48:51], v[168:171], v[188:191], 0
	v_mfma_f32_16x16x32_bf16 v[48:51], v[172:175], v[192:195], v[48:51]
	v_mfma_f32_16x16x32_bf16 v[40:43], v[176:179], v[188:191], 0
	v_mfma_f32_16x16x32_bf16 v[40:43], v[184:187], v[192:195], v[40:43]
	v_mfma_f32_16x16x32_bf16 v[32:35], v[168:171], v[196:199], 0
	v_mfma_f32_16x16x32_bf16 v[32:35], v[172:175], v[200:203], v[32:35]
	v_mfma_f32_16x16x32_bf16 v[24:27], v[176:179], v[196:199], 0
	v_mfma_f32_16x16x32_bf16 v[24:27], v[184:187], v[200:203], v[24:27]
	v_mfma_f32_16x16x32_bf16 v[16:19], v[168:171], v[204:207], 0
	v_mfma_f32_16x16x32_bf16 v[16:19], v[172:175], v[208:211], v[16:19]
	v_mfma_f32_16x16x32_bf16 v[8:11], v[176:179], v[204:207], 0
	v_mfma_f32_16x16x32_bf16 v[8:11], v[184:187], v[208:211], v[8:11]
	v_mfma_f32_16x16x32_bf16 v[4:7], v[168:171], v[212:215], 0
	v_mfma_f32_16x16x32_bf16 v[4:7], v[172:175], v[216:219], v[4:7]
	v_mfma_f32_16x16x32_bf16 v[0:3], v[176:179], v[212:215], 0
	v_mfma_f32_16x16x32_bf16 v[0:3], v[184:187], v[216:219], v[0:3]
	s_setprio 0
	s_barrier
	s_branch .Lmid_gemm5
.LBB0_804:
	ds_read_b128 v[152:155], v149
	ds_read_b128 v[156:159], v149 offset:1024
	ds_read_b128 v[160:163], v149 offset:2048
	ds_read_b128 v[164:167], v149 offset:3072
	ds_read_b128 v[168:171], v150
	ds_read_b128 v[172:175], v150 offset:1024
	ds_read_b128 v[176:179], v150 offset:2048
	ds_read_b128 v[184:187], v150 offset:3072
	s_add_u32 s54, s52, 0x100
	s_addc_u32 s55, s53, 0
	s_cmp_eq_u32 s86, 40
	s_cselect_b32 s59, s13, s55
	s_cselect_b32 s58, s12, s54
	s_cselect_b32 s57, s49, s85
	s_cselect_b32 s56, s48, s84
	v_lshl_add_u64 v[144:145], s[52:53], 0, v[136:137]
	s_add_i32 m0, s63, 0xc000
	ds_read_b128 v[188:191], v151
	ds_read_b128 v[192:195], v151 offset:1024
	ds_read_b128 v[196:199], v151 offset:2048
	ds_read_b128 v[200:203], v151 offset:3072
	ds_read_b128 v[204:207], v151 offset:4096
	ds_read_b128 v[208:211], v151 offset:5120
	ds_read_b128 v[212:215], v151 offset:6144
	ds_read_b128 v[216:219], v151 offset:7168
	global_load_lds_dwordx4 v[144:145], off nt
	v_lshl_add_u64 v[144:145], s[52:53], 0, v[138:139]
	s_add_i32 m0, s63, 0xe000
	s_nop 0
	global_load_lds_dwordx4 v[144:145], off nt
	s_waitcnt vmcnt(8)
	s_waitcnt lgkmcnt(0)
	s_barrier
	s_setprio 1
	s_waitcnt lgkmcnt(0)
	v_mfma_f32_16x16x32_bf16 v[124:127], v[152:155], v[188:191], v[124:127]
	v_mfma_f32_16x16x32_bf16 v[124:127], v[156:159], v[192:195], v[124:127]
	v_mfma_f32_16x16x32_bf16 v[120:123], v[160:163], v[188:191], v[120:123]
	v_mfma_f32_16x16x32_bf16 v[120:123], v[164:167], v[192:195], v[120:123]
	v_mfma_f32_16x16x32_bf16 v[116:119], v[152:155], v[196:199], v[116:119]
	v_mfma_f32_16x16x32_bf16 v[116:119], v[156:159], v[200:203], v[116:119]
	v_mfma_f32_16x16x32_bf16 v[108:111], v[160:163], v[196:199], v[108:111]
	v_mfma_f32_16x16x32_bf16 v[108:111], v[164:167], v[200:203], v[108:111]
	v_mfma_f32_16x16x32_bf16 v[100:103], v[152:155], v[204:207], v[100:103]
	v_mfma_f32_16x16x32_bf16 v[100:103], v[156:159], v[208:211], v[100:103]
	v_mfma_f32_16x16x32_bf16 v[92:95], v[160:163], v[204:207], v[92:95]
	v_mfma_f32_16x16x32_bf16 v[92:95], v[164:167], v[208:211], v[92:95]
	v_mfma_f32_16x16x32_bf16 v[84:87], v[152:155], v[212:215], v[84:87]
	v_mfma_f32_16x16x32_bf16 v[84:87], v[156:159], v[216:219], v[84:87]
	v_mfma_f32_16x16x32_bf16 v[76:79], v[160:163], v[212:215], v[76:79]
	v_mfma_f32_16x16x32_bf16 v[76:79], v[164:167], v[216:219], v[76:79]
	v_mfma_f32_16x16x32_bf16 v[112:115], v[168:171], v[188:191], v[112:115]
	v_mfma_f32_16x16x32_bf16 v[112:115], v[172:175], v[192:195], v[112:115]
	v_mfma_f32_16x16x32_bf16 v[104:107], v[176:179], v[188:191], v[104:107]
	v_mfma_f32_16x16x32_bf16 v[104:107], v[184:187], v[192:195], v[104:107]
	v_mfma_f32_16x16x32_bf16 v[96:99], v[168:171], v[196:199], v[96:99]
	v_mfma_f32_16x16x32_bf16 v[96:99], v[172:175], v[200:203], v[96:99]
	v_mfma_f32_16x16x32_bf16 v[88:91], v[176:179], v[196:199], v[88:91]
	v_mfma_f32_16x16x32_bf16 v[88:91], v[184:187], v[200:203], v[88:91]
	v_mfma_f32_16x16x32_bf16 v[80:83], v[168:171], v[204:207], v[80:83]
	v_mfma_f32_16x16x32_bf16 v[80:83], v[172:175], v[208:211], v[80:83]
	v_mfma_f32_16x16x32_bf16 v[72:75], v[176:179], v[204:207], v[72:75]
	v_mfma_f32_16x16x32_bf16 v[72:75], v[184:187], v[208:211], v[72:75]
	v_mfma_f32_16x16x32_bf16 v[68:71], v[168:171], v[212:215], v[68:71]
	v_mfma_f32_16x16x32_bf16 v[68:71], v[172:175], v[216:219], v[68:71]
	v_mfma_f32_16x16x32_bf16 v[64:67], v[176:179], v[212:215], v[64:67]
	v_mfma_f32_16x16x32_bf16 v[64:67], v[184:187], v[216:219], v[64:67]
	s_setprio 0
	s_barrier
	s_add_i32 s52, s70, s62
	v_lshl_add_u64 v[144:145], s[56:57], 0, v[130:131]
	s_mov_b32 m0, s52
	ds_read_b128 v[188:191], v151 offset:16384
	ds_read_b128 v[192:195], v151 offset:17408
	ds_read_b128 v[196:199], v151 offset:18432
	ds_read_b128 v[200:203], v151 offset:19456
	ds_read_b128 v[204:207], v151 offset:20480
	ds_read_b128 v[208:211], v151 offset:21504
	ds_read_b128 v[212:215], v151 offset:22528
	ds_read_b128 v[216:219], v151 offset:23552
	global_load_lds_dwordx4 v[144:145], off
	s_add_i32 m0, s52, 0x2000
	s_add_u32 s52, s56, 0xb0000
	v_lshl_add_u64 v[220:221], s[56:57], 0, v[134:135]
	s_addc_u32 s53, s57, 0
	s_add_i32 s79, s71, s62
	global_load_lds_dwordx4 v[220:221], off
	v_lshl_add_u64 v[222:223], s[52:53], 0, v[130:131]
	s_mov_b32 m0, s79
	v_lshl_add_u64 v[224:225], s[58:59], 0, v[132:133]
	global_load_lds_dwordx4 v[222:223], off
	v_lshl_add_u64 v[222:223], s[52:53], 0, v[134:135]
	s_add_i32 m0, s79, 0x2000
	s_nop 0
	global_load_lds_dwordx4 v[222:223], off
	v_lshl_add_u64 v[222:223], s[58:59], 0, v[128:129]
	s_mov_b32 m0, s63
	s_nop 0
	global_load_lds_dwordx4 v[222:223], off nt
	s_mov_b32 m0, s64
	s_nop 0
	global_load_lds_dwordx4 v[224:225], off nt
	s_waitcnt vmcnt(8)
	s_waitcnt lgkmcnt(0)
	s_barrier
	s_setprio 1
	s_waitcnt lgkmcnt(0)
	v_mfma_f32_16x16x32_bf16 v[60:63], v[152:155], v[188:191], v[60:63]
	v_mfma_f32_16x16x32_bf16 v[60:63], v[156:159], v[192:195], v[60:63]
	v_mfma_f32_16x16x32_bf16 v[56:59], v[160:163], v[188:191], v[56:59]
	v_mfma_f32_16x16x32_bf16 v[56:59], v[164:167], v[192:195], v[56:59]
	v_mfma_f32_16x16x32_bf16 v[52:55], v[152:155], v[196:199], v[52:55]
	v_mfma_f32_16x16x32_bf16 v[52:55], v[156:159], v[200:203], v[52:55]
	v_mfma_f32_16x16x32_bf16 v[44:47], v[160:163], v[196:199], v[44:47]
	v_mfma_f32_16x16x32_bf16 v[44:47], v[164:167], v[200:203], v[44:47]
	v_mfma_f32_16x16x32_bf16 v[36:39], v[152:155], v[204:207], v[36:39]
	v_mfma_f32_16x16x32_bf16 v[36:39], v[156:159], v[208:211], v[36:39]
	v_mfma_f32_16x16x32_bf16 v[28:31], v[160:163], v[204:207], v[28:31]
	v_mfma_f32_16x16x32_bf16 v[28:31], v[164:167], v[208:211], v[28:31]
	v_mfma_f32_16x16x32_bf16 v[20:23], v[152:155], v[212:215], v[20:23]
	v_mfma_f32_16x16x32_bf16 v[20:23], v[156:159], v[216:219], v[20:23]
	v_mfma_f32_16x16x32_bf16 v[12:15], v[160:163], v[212:215], v[12:15]
	v_mfma_f32_16x16x32_bf16 v[12:15], v[164:167], v[216:219], v[12:15]
	v_mfma_f32_16x16x32_bf16 v[48:51], v[168:171], v[188:191], v[48:51]
	v_mfma_f32_16x16x32_bf16 v[48:51], v[172:175], v[192:195], v[48:51]
	v_mfma_f32_16x16x32_bf16 v[40:43], v[176:179], v[188:191], v[40:43]
	v_mfma_f32_16x16x32_bf16 v[40:43], v[184:187], v[192:195], v[40:43]
	v_mfma_f32_16x16x32_bf16 v[32:35], v[168:171], v[196:199], v[32:35]
	v_mfma_f32_16x16x32_bf16 v[32:35], v[172:175], v[200:203], v[32:35]
	v_mfma_f32_16x16x32_bf16 v[24:27], v[176:179], v[196:199], v[24:27]
	v_mfma_f32_16x16x32_bf16 v[24:27], v[184:187], v[200:203], v[24:27]
	v_mfma_f32_16x16x32_bf16 v[16:19], v[168:171], v[204:207], v[16:19]
	v_mfma_f32_16x16x32_bf16 v[16:19], v[172:175], v[208:211], v[16:19]
	v_mfma_f32_16x16x32_bf16 v[8:11], v[176:179], v[204:207], v[8:11]
	v_mfma_f32_16x16x32_bf16 v[8:11], v[184:187], v[208:211], v[8:11]
	v_mfma_f32_16x16x32_bf16 v[4:7], v[168:171], v[212:215], v[4:7]
	v_mfma_f32_16x16x32_bf16 v[4:7], v[172:175], v[216:219], v[4:7]
	v_mfma_f32_16x16x32_bf16 v[0:3], v[176:179], v[212:215], v[0:3]
	v_mfma_f32_16x16x32_bf16 v[0:3], v[184:187], v[216:219], v[0:3]
	s_setprio 0
	s_barrier
.Lmid_gemm5:
	s_add_i32 s79, 0, 0x18000
	s_add_i32 s87, 0, 0x1c000
	v_add_u32_e32 v164, s79, v147
	v_add_u32_e32 v181, s87, v147
	ds_read_b128 v[152:155], v164
	ds_read_b128 v[156:159], v164 offset:1024
	ds_read_b128 v[160:163], v164 offset:2048
	ds_read_b128 v[164:167], v164 offset:3072
	ds_read_b128 v[168:171], v181
	ds_read_b128 v[172:175], v181 offset:1024
	ds_read_b128 v[176:179], v181 offset:2048
	ds_read_b128 v[184:187], v181 offset:3072
	s_add_u32 s52, s58, 0xb0000
	s_addc_u32 s53, s59, 0
	s_mov_b32 m0, s65
	v_lshl_add_u64 v[226:227], s[52:53], 0, v[128:129]
	ds_read_b128 v[188:191], v151 offset:32768
	ds_read_b128 v[192:195], v151 offset:33792
	ds_read_b128 v[196:199], v151 offset:34816
	ds_read_b128 v[200:203], v151 offset:35840
	ds_read_b128 v[204:207], v151 offset:36864
	ds_read_b128 v[208:211], v151 offset:37888
	ds_read_b128 v[212:215], v151 offset:38912
	ds_read_b128 v[216:219], v151 offset:39936
	global_load_lds_dwordx4 v[226:227], off nt
	v_lshl_add_u64 v[226:227], s[52:53], 0, v[132:133]
	s_mov_b32 m0, s66
	s_nop 0
	global_load_lds_dwordx4 v[226:227], off nt
	s_waitcnt vmcnt(8)
	s_waitcnt lgkmcnt(0)
	s_barrier
	s_setprio 1
	s_waitcnt lgkmcnt(0)
	v_mfma_f32_16x16x32_bf16 v[124:127], v[152:155], v[188:191], v[124:127]
	v_mfma_f32_16x16x32_bf16 v[124:127], v[156:159], v[192:195], v[124:127]
	v_mfma_f32_16x16x32_bf16 v[120:123], v[160:163], v[188:191], v[120:123]
	v_mfma_f32_16x16x32_bf16 v[120:123], v[164:167], v[192:195], v[120:123]
	v_mfma_f32_16x16x32_bf16 v[116:119], v[152:155], v[196:199], v[116:119]
	v_mfma_f32_16x16x32_bf16 v[116:119], v[156:159], v[200:203], v[116:119]
	v_mfma_f32_16x16x32_bf16 v[108:111], v[160:163], v[196:199], v[108:111]
	v_mfma_f32_16x16x32_bf16 v[108:111], v[164:167], v[200:203], v[108:111]
	v_mfma_f32_16x16x32_bf16 v[100:103], v[152:155], v[204:207], v[100:103]
	v_mfma_f32_16x16x32_bf16 v[100:103], v[156:159], v[208:211], v[100:103]
	v_mfma_f32_16x16x32_bf16 v[92:95], v[160:163], v[204:207], v[92:95]
	v_mfma_f32_16x16x32_bf16 v[92:95], v[164:167], v[208:211], v[92:95]
	v_mfma_f32_16x16x32_bf16 v[84:87], v[152:155], v[212:215], v[84:87]
	v_mfma_f32_16x16x32_bf16 v[84:87], v[156:159], v[216:219], v[84:87]
	v_mfma_f32_16x16x32_bf16 v[76:79], v[160:163], v[212:215], v[76:79]
	v_mfma_f32_16x16x32_bf16 v[76:79], v[164:167], v[216:219], v[76:79]
	v_mfma_f32_16x16x32_bf16 v[112:115], v[168:171], v[188:191], v[112:115]
	v_mfma_f32_16x16x32_bf16 v[112:115], v[172:175], v[192:195], v[112:115]
	v_mfma_f32_16x16x32_bf16 v[104:107], v[176:179], v[188:191], v[104:107]
	v_mfma_f32_16x16x32_bf16 v[104:107], v[184:187], v[192:195], v[104:107]
	v_mfma_f32_16x16x32_bf16 v[96:99], v[168:171], v[196:199], v[96:99]
	v_mfma_f32_16x16x32_bf16 v[96:99], v[172:175], v[200:203], v[96:99]
	v_mfma_f32_16x16x32_bf16 v[88:91], v[176:179], v[196:199], v[88:91]
	v_mfma_f32_16x16x32_bf16 v[88:91], v[184:187], v[200:203], v[88:91]
	v_mfma_f32_16x16x32_bf16 v[80:83], v[168:171], v[204:207], v[80:83]
	v_mfma_f32_16x16x32_bf16 v[80:83], v[172:175], v[208:211], v[80:83]
	v_mfma_f32_16x16x32_bf16 v[72:75], v[176:179], v[204:207], v[72:75]
	v_mfma_f32_16x16x32_bf16 v[72:75], v[184:187], v[208:211], v[72:75]
	v_mfma_f32_16x16x32_bf16 v[68:71], v[168:171], v[212:215], v[68:71]
	v_mfma_f32_16x16x32_bf16 v[68:71], v[172:175], v[216:219], v[68:71]
	v_mfma_f32_16x16x32_bf16 v[64:67], v[176:179], v[212:215], v[64:67]
	v_mfma_f32_16x16x32_bf16 v[64:67], v[184:187], v[216:219], v[64:67]
	s_setprio 0
	s_barrier
	s_add_i32 s52, s79, s62
	v_lshl_add_u64 v[144:145], v[144:145], 0, s[16:17]
	s_mov_b32 m0, s52
	ds_read_b128 v[188:191], v151 offset:49152
	ds_read_b128 v[192:195], v151 offset:50176
	ds_read_b128 v[196:199], v151 offset:51200
	ds_read_b128 v[200:203], v151 offset:52224
	ds_read_b128 v[204:207], v151 offset:53248
	ds_read_b128 v[208:211], v151 offset:54272
	ds_read_b128 v[212:215], v151 offset:55296
	ds_read_b128 v[216:219], v151 offset:56320
	global_load_lds_dwordx4 v[144:145], off
	s_add_i32 m0, s52, 0x2000
	s_add_u32 s52, s56, 0xb0080
	v_lshl_add_u64 v[144:145], v[220:221], 0, s[16:17]
	s_addc_u32 s53, s57, 0
	s_add_i32 s56, s87, s62
	global_load_lds_dwordx4 v[144:145], off
	v_lshl_add_u64 v[144:145], s[52:53], 0, v[130:131]
	s_mov_b32 m0, s56
	s_nop 0
	global_load_lds_dwordx4 v[144:145], off
	v_lshl_add_u64 v[144:145], s[52:53], 0, v[134:135]
	s_add_i32 m0, s56, 0x2000
	s_nop 0
	global_load_lds_dwordx4 v[144:145], off
	v_lshl_add_u64 v[144:145], v[222:223], 0, s[16:17]
	s_mov_b32 m0, s68
	s_nop 0
	global_load_lds_dwordx4 v[144:145], off nt
	v_lshl_add_u64 v[144:145], v[224:225], 0, s[16:17]
	s_mov_b32 m0, s69
	s_nop 0
	global_load_lds_dwordx4 v[144:145], off nt
	s_waitcnt vmcnt(8)
	s_waitcnt lgkmcnt(0)
	s_barrier
	s_setprio 1
	s_waitcnt lgkmcnt(0)
	v_mfma_f32_16x16x32_bf16 v[60:63], v[152:155], v[188:191], v[60:63]
	v_mfma_f32_16x16x32_bf16 v[60:63], v[156:159], v[192:195], v[60:63]
	v_mfma_f32_16x16x32_bf16 v[56:59], v[160:163], v[188:191], v[56:59]
	v_mfma_f32_16x16x32_bf16 v[56:59], v[164:167], v[192:195], v[56:59]
	v_mfma_f32_16x16x32_bf16 v[52:55], v[152:155], v[196:199], v[52:55]
	v_mfma_f32_16x16x32_bf16 v[52:55], v[156:159], v[200:203], v[52:55]
	v_mfma_f32_16x16x32_bf16 v[44:47], v[160:163], v[196:199], v[44:47]
	v_mfma_f32_16x16x32_bf16 v[44:47], v[164:167], v[200:203], v[44:47]
	v_mfma_f32_16x16x32_bf16 v[36:39], v[152:155], v[204:207], v[36:39]
	v_mfma_f32_16x16x32_bf16 v[36:39], v[156:159], v[208:211], v[36:39]
	v_mfma_f32_16x16x32_bf16 v[28:31], v[160:163], v[204:207], v[28:31]
	v_mfma_f32_16x16x32_bf16 v[28:31], v[164:167], v[208:211], v[28:31]
	v_mfma_f32_16x16x32_bf16 v[20:23], v[152:155], v[212:215], v[20:23]
	v_mfma_f32_16x16x32_bf16 v[20:23], v[156:159], v[216:219], v[20:23]
	v_mfma_f32_16x16x32_bf16 v[12:15], v[160:163], v[212:215], v[12:15]
	v_mfma_f32_16x16x32_bf16 v[12:15], v[164:167], v[216:219], v[12:15]
	v_mfma_f32_16x16x32_bf16 v[48:51], v[168:171], v[188:191], v[48:51]
	v_mfma_f32_16x16x32_bf16 v[48:51], v[172:175], v[192:195], v[48:51]
	v_mfma_f32_16x16x32_bf16 v[40:43], v[176:179], v[188:191], v[40:43]
	v_mfma_f32_16x16x32_bf16 v[40:43], v[184:187], v[192:195], v[40:43]
	v_mfma_f32_16x16x32_bf16 v[32:35], v[168:171], v[196:199], v[32:35]
	v_mfma_f32_16x16x32_bf16 v[32:35], v[172:175], v[200:203], v[32:35]
	v_mfma_f32_16x16x32_bf16 v[24:27], v[176:179], v[196:199], v[24:27]
	v_mfma_f32_16x16x32_bf16 v[24:27], v[184:187], v[200:203], v[24:27]
	v_mfma_f32_16x16x32_bf16 v[16:19], v[168:171], v[204:207], v[16:19]
	v_mfma_f32_16x16x32_bf16 v[16:19], v[172:175], v[208:211], v[16:19]
	v_mfma_f32_16x16x32_bf16 v[8:11], v[176:179], v[204:207], v[8:11]
	v_mfma_f32_16x16x32_bf16 v[8:11], v[184:187], v[208:211], v[8:11]
	v_mfma_f32_16x16x32_bf16 v[4:7], v[168:171], v[212:215], v[4:7]
	v_mfma_f32_16x16x32_bf16 v[4:7], v[172:175], v[216:219], v[4:7]
	v_mfma_f32_16x16x32_bf16 v[0:3], v[176:179], v[212:215], v[0:3]
	v_mfma_f32_16x16x32_bf16 v[0:3], v[184:187], v[216:219], v[0:3]
	s_setprio 0
	s_barrier
	s_add_i32 s86, s86, 2
	s_add_u32 s84, s84, 0x100
	s_addc_u32 s85, s85, 0
	s_cmp_gt_u32 s86, 41
	s_mov_b64 s[52:53], s[54:55]
	s_cbranch_scc0 .LBB0_804
	s_and_b64 vcc, exec, s[18:19]
	s_cbranch_vccz .LBB0_807
	s_barrier

.LBB0_1030:
	s_add_u32 s86, s56, 0x100
	s_addc_u32 s87, s57, 0
	s_mov_b32 s88, -2
	ds_read_b128 v[152:155], v149
	ds_read_b128 v[156:159], v149 offset:1024
	ds_read_b128 v[160:163], v149 offset:2048
	ds_read_b128 v[164:167], v149 offset:3072
	ds_read_b128 v[168:171], v150
	ds_read_b128 v[172:175], v150 offset:1024
	ds_read_b128 v[176:179], v150 offset:2048
	ds_read_b128 v[184:187], v150 offset:3072
	s_add_u32 s56, s54, 0x100
	s_addc_u32 s57, s55, 0
	s_cmp_eq_u32 s88, 40
	s_cselect_b32 s61, s13, s57
	s_cselect_b32 s60, s12, s56
	s_cselect_b32 s59, s53, s87
	s_cselect_b32 s58, s52, s86
	v_lshl_add_u64 v[144:145], s[54:55], 0, v[136:137]
	s_add_i32 m0, s65, 0xc000
	ds_read_b128 v[188:191], v151
	ds_read_b128 v[192:195], v151 offset:1024
	ds_read_b128 v[196:199], v151 offset:2048
	ds_read_b128 v[200:203], v151 offset:3072
	ds_read_b128 v[204:207], v151 offset:4096
	ds_read_b128 v[208:211], v151 offset:5120
	ds_read_b128 v[212:215], v151 offset:6144
	ds_read_b128 v[216:219], v151 offset:7168
	global_load_lds_dwordx4 v[144:145], off nt
	v_lshl_add_u64 v[144:145], s[54:55], 0, v[138:139]
	s_add_i32 m0, s65, 0xe000
	s_nop 0
	global_load_lds_dwordx4 v[144:145], off nt
	s_waitcnt vmcnt(8)
	s_waitcnt lgkmcnt(0)
	s_barrier
	s_setprio 1
	s_waitcnt lgkmcnt(0)
	v_mfma_f32_16x16x32_bf16 v[124:127], v[152:155], v[188:191], 0
	v_mfma_f32_16x16x32_bf16 v[124:127], v[156:159], v[192:195], v[124:127]
	v_mfma_f32_16x16x32_bf16 v[120:123], v[160:163], v[188:191], 0
	v_mfma_f32_16x16x32_bf16 v[120:123], v[164:167], v[192:195], v[120:123]
	v_mfma_f32_16x16x32_bf16 v[116:119], v[152:155], v[196:199], 0
	v_mfma_f32_16x16x32_bf16 v[116:119], v[156:159], v[200:203], v[116:119]
	v_mfma_f32_16x16x32_bf16 v[108:111], v[160:163], v[196:199], 0
	v_mfma_f32_16x16x32_bf16 v[108:111], v[164:167], v[200:203], v[108:111]
	v_mfma_f32_16x16x32_bf16 v[100:103], v[152:155], v[204:207], 0
	v_mfma_f32_16x16x32_bf16 v[100:103], v[156:159], v[208:211], v[100:103]
	v_mfma_f32_16x16x32_bf16 v[92:95], v[160:163], v[204:207], 0
	v_mfma_f32_16x16x32_bf16 v[92:95], v[164:167], v[208:211], v[92:95]
	v_mfma_f32_16x16x32_bf16 v[84:87], v[152:155], v[212:215], 0
	v_mfma_f32_16x16x32_bf16 v[84:87], v[156:159], v[216:219], v[84:87]
	v_mfma_f32_16x16x32_bf16 v[76:79], v[160:163], v[212:215], 0
	v_mfma_f32_16x16x32_bf16 v[76:79], v[164:167], v[216:219], v[76:79]
	v_mfma_f32_16x16x32_bf16 v[112:115], v[168:171], v[188:191], 0
	v_mfma_f32_16x16x32_bf16 v[112:115], v[172:175], v[192:195], v[112:115]
	v_mfma_f32_16x16x32_bf16 v[104:107], v[176:179], v[188:191], 0
	v_mfma_f32_16x16x32_bf16 v[104:107], v[184:187], v[192:195], v[104:107]
	v_mfma_f32_16x16x32_bf16 v[96:99], v[168:171], v[196:199], 0
	v_mfma_f32_16x16x32_bf16 v[96:99], v[172:175], v[200:203], v[96:99]
	v_mfma_f32_16x16x32_bf16 v[88:91], v[176:179], v[196:199], 0
	v_mfma_f32_16x16x32_bf16 v[88:91], v[184:187], v[200:203], v[88:91]
	v_mfma_f32_16x16x32_bf16 v[80:83], v[168:171], v[204:207], 0
	v_mfma_f32_16x16x32_bf16 v[80:83], v[172:175], v[208:211], v[80:83]
	v_mfma_f32_16x16x32_bf16 v[72:75], v[176:179], v[204:207], 0
	v_mfma_f32_16x16x32_bf16 v[72:75], v[184:187], v[208:211], v[72:75]
	v_mfma_f32_16x16x32_bf16 v[68:71], v[168:171], v[212:215], 0
	v_mfma_f32_16x16x32_bf16 v[68:71], v[172:175], v[216:219], v[68:71]
	v_mfma_f32_16x16x32_bf16 v[64:67], v[176:179], v[212:215], 0
	v_mfma_f32_16x16x32_bf16 v[64:67], v[184:187], v[216:219], v[64:67]
	s_setprio 0
	s_barrier
	s_add_i32 s54, s72, s64
	v_lshl_add_u64 v[144:145], s[58:59], 0, v[130:131]
	s_mov_b32 m0, s54
	ds_read_b128 v[188:191], v151 offset:16384
	ds_read_b128 v[192:195], v151 offset:17408
	ds_read_b128 v[196:199], v151 offset:18432
	ds_read_b128 v[200:203], v151 offset:19456
	ds_read_b128 v[204:207], v151 offset:20480
	ds_read_b128 v[208:211], v151 offset:21504
	ds_read_b128 v[212:215], v151 offset:22528
	ds_read_b128 v[216:219], v151 offset:23552
	global_load_lds_dwordx4 v[144:145], off
	s_add_i32 m0, s54, 0x2000
	s_add_u32 s54, s58, 0xb0000
	v_lshl_add_u64 v[220:221], s[58:59], 0, v[134:135]
	s_addc_u32 s55, s59, 0
	s_add_i32 s79, s73, s64
	global_load_lds_dwordx4 v[220:221], off
	v_lshl_add_u64 v[222:223], s[54:55], 0, v[130:131]
	s_mov_b32 m0, s79
	v_lshl_add_u64 v[224:225], s[60:61], 0, v[132:133]
	global_load_lds_dwordx4 v[222:223], off
	v_lshl_add_u64 v[222:223], s[54:55], 0, v[134:135]
	s_add_i32 m0, s79, 0x2000
	s_nop 0
	global_load_lds_dwordx4 v[222:223], off
	v_lshl_add_u64 v[222:223], s[60:61], 0, v[128:129]
	s_mov_b32 m0, s65
	s_nop 0
	global_load_lds_dwordx4 v[222:223], off nt
	s_mov_b32 m0, s66
	s_nop 0
	global_load_lds_dwordx4 v[224:225], off nt
	s_waitcnt vmcnt(8)
	s_waitcnt lgkmcnt(0)
	s_barrier
	s_setprio 1
	s_waitcnt lgkmcnt(0)
	v_mfma_f32_16x16x32_bf16 v[60:63], v[152:155], v[188:191], 0
	v_mfma_f32_16x16x32_bf16 v[60:63], v[156:159], v[192:195], v[60:63]
	v_mfma_f32_16x16x32_bf16 v[56:59], v[160:163], v[188:191], 0
	v_mfma_f32_16x16x32_bf16 v[56:59], v[164:167], v[192:195], v[56:59]
	v_mfma_f32_16x16x32_bf16 v[52:55], v[152:155], v[196:199], 0
	v_mfma_f32_16x16x32_bf16 v[52:55], v[156:159], v[200:203], v[52:55]
	v_mfma_f32_16x16x32_bf16 v[44:47], v[160:163], v[196:199], 0
	v_mfma_f32_16x16x32_bf16 v[44:47], v[164:167], v[200:203], v[44:47]
	v_mfma_f32_16x16x32_bf16 v[36:39], v[152:155], v[204:207], 0
	v_mfma_f32_16x16x32_bf16 v[36:39], v[156:159], v[208:211], v[36:39]
	v_mfma_f32_16x16x32_bf16 v[28:31], v[160:163], v[204:207], 0
	v_mfma_f32_16x16x32_bf16 v[28:31], v[164:167], v[208:211], v[28:31]
	v_mfma_f32_16x16x32_bf16 v[20:23], v[152:155], v[212:215], 0
	v_mfma_f32_16x16x32_bf16 v[20:23], v[156:159], v[216:219], v[20:23]
	v_mfma_f32_16x16x32_bf16 v[12:15], v[160:163], v[212:215], 0
	v_mfma_f32_16x16x32_bf16 v[12:15], v[164:167], v[216:219], v[12:15]
	v_mfma_f32_16x16x32_bf16 v[48:51], v[168:171], v[188:191], 0
	v_mfma_f32_16x16x32_bf16 v[48:51], v[172:175], v[192:195], v[48:51]
	v_mfma_f32_16x16x32_bf16 v[40:43], v[176:179], v[188:191], 0
	v_mfma_f32_16x16x32_bf16 v[40:43], v[184:187], v[192:195], v[40:43]
	v_mfma_f32_16x16x32_bf16 v[32:35], v[168:171], v[196:199], 0
	v_mfma_f32_16x16x32_bf16 v[32:35], v[172:175], v[200:203], v[32:35]
	v_mfma_f32_16x16x32_bf16 v[24:27], v[176:179], v[196:199], 0
	v_mfma_f32_16x16x32_bf16 v[24:27], v[184:187], v[200:203], v[24:27]
	v_mfma_f32_16x16x32_bf16 v[16:19], v[168:171], v[204:207], 0
	v_mfma_f32_16x16x32_bf16 v[16:19], v[172:175], v[208:211], v[16:19]
	v_mfma_f32_16x16x32_bf16 v[8:11], v[176:179], v[204:207], 0
	v_mfma_f32_16x16x32_bf16 v[8:11], v[184:187], v[208:211], v[8:11]
	v_mfma_f32_16x16x32_bf16 v[4:7], v[168:171], v[212:215], 0
	v_mfma_f32_16x16x32_bf16 v[4:7], v[172:175], v[216:219], v[4:7]
	v_mfma_f32_16x16x32_bf16 v[0:3], v[176:179], v[212:215], 0
	v_mfma_f32_16x16x32_bf16 v[0:3], v[184:187], v[216:219], v[0:3]
	s_setprio 0
	s_barrier
	s_branch .Lmid_gemm8
.LBB0_1031:
	ds_read_b128 v[152:155], v149
	ds_read_b128 v[156:159], v149 offset:1024
	ds_read_b128 v[160:163], v149 offset:2048
	ds_read_b128 v[164:167], v149 offset:3072
	ds_read_b128 v[168:171], v150
	ds_read_b128 v[172:175], v150 offset:1024
	ds_read_b128 v[176:179], v150 offset:2048
	ds_read_b128 v[184:187], v150 offset:3072
	s_add_u32 s56, s54, 0x100
	s_addc_u32 s57, s55, 0
	s_cmp_eq_u32 s88, 40
	s_cselect_b32 s61, s13, s57
	s_cselect_b32 s60, s12, s56
	s_cselect_b32 s59, s53, s87
	s_cselect_b32 s58, s52, s86
	v_lshl_add_u64 v[144:145], s[54:55], 0, v[136:137]
	s_add_i32 m0, s65, 0xc000
	ds_read_b128 v[188:191], v151
	ds_read_b128 v[192:195], v151 offset:1024
	ds_read_b128 v[196:199], v151 offset:2048
	ds_read_b128 v[200:203], v151 offset:3072
	ds_read_b128 v[204:207], v151 offset:4096
	ds_read_b128 v[208:211], v151 offset:5120
	ds_read_b128 v[212:215], v151 offset:6144
	ds_read_b128 v[216:219], v151 offset:7168
	global_load_lds_dwordx4 v[144:145], off nt
	v_lshl_add_u64 v[144:145], s[54:55], 0, v[138:139]
	s_add_i32 m0, s65, 0xe000
	s_nop 0
	global_load_lds_dwordx4 v[144:145], off nt
	s_waitcnt vmcnt(8)
	s_waitcnt lgkmcnt(0)
	s_barrier
	s_setprio 1
	s_waitcnt lgkmcnt(0)
	v_mfma_f32_16x16x32_bf16 v[124:127], v[152:155], v[188:191], v[124:127]
	v_mfma_f32_16x16x32_bf16 v[124:127], v[156:159], v[192:195], v[124:127]
	v_mfma_f32_16x16x32_bf16 v[120:123], v[160:163], v[188:191], v[120:123]
	v_mfma_f32_16x16x32_bf16 v[120:123], v[164:167], v[192:195], v[120:123]
	v_mfma_f32_16x16x32_bf16 v[116:119], v[152:155], v[196:199], v[116:119]
	v_mfma_f32_16x16x32_bf16 v[116:119], v[156:159], v[200:203], v[116:119]
	v_mfma_f32_16x16x32_bf16 v[108:111], v[160:163], v[196:199], v[108:111]
	v_mfma_f32_16x16x32_bf16 v[108:111], v[164:167], v[200:203], v[108:111]
	v_mfma_f32_16x16x32_bf16 v[100:103], v[152:155], v[204:207], v[100:103]
	v_mfma_f32_16x16x32_bf16 v[100:103], v[156:159], v[208:211], v[100:103]
	v_mfma_f32_16x16x32_bf16 v[92:95], v[160:163], v[204:207], v[92:95]
	v_mfma_f32_16x16x32_bf16 v[92:95], v[164:167], v[208:211], v[92:95]
	v_mfma_f32_16x16x32_bf16 v[84:87], v[152:155], v[212:215], v[84:87]
	v_mfma_f32_16x16x32_bf16 v[84:87], v[156:159], v[216:219], v[84:87]
	v_mfma_f32_16x16x32_bf16 v[76:79], v[160:163], v[212:215], v[76:79]
	v_mfma_f32_16x16x32_bf16 v[76:79], v[164:167], v[216:219], v[76:79]
	v_mfma_f32_16x16x32_bf16 v[112:115], v[168:171], v[188:191], v[112:115]
	v_mfma_f32_16x16x32_bf16 v[112:115], v[172:175], v[192:195], v[112:115]
	v_mfma_f32_16x16x32_bf16 v[104:107], v[176:179], v[188:191], v[104:107]
	v_mfma_f32_16x16x32_bf16 v[104:107], v[184:187], v[192:195], v[104:107]
	v_mfma_f32_16x16x32_bf16 v[96:99], v[168:171], v[196:199], v[96:99]
	v_mfma_f32_16x16x32_bf16 v[96:99], v[172:175], v[200:203], v[96:99]
	v_mfma_f32_16x16x32_bf16 v[88:91], v[176:179], v[196:199], v[88:91]
	v_mfma_f32_16x16x32_bf16 v[88:91], v[184:187], v[200:203], v[88:91]
	v_mfma_f32_16x16x32_bf16 v[80:83], v[168:171], v[204:207], v[80:83]
	v_mfma_f32_16x16x32_bf16 v[80:83], v[172:175], v[208:211], v[80:83]
	v_mfma_f32_16x16x32_bf16 v[72:75], v[176:179], v[204:207], v[72:75]
	v_mfma_f32_16x16x32_bf16 v[72:75], v[184:187], v[208:211], v[72:75]
	v_mfma_f32_16x16x32_bf16 v[68:71], v[168:171], v[212:215], v[68:71]
	v_mfma_f32_16x16x32_bf16 v[68:71], v[172:175], v[216:219], v[68:71]
	v_mfma_f32_16x16x32_bf16 v[64:67], v[176:179], v[212:215], v[64:67]
	v_mfma_f32_16x16x32_bf16 v[64:67], v[184:187], v[216:219], v[64:67]
	s_setprio 0
	s_barrier
	s_add_i32 s54, s72, s64
	v_lshl_add_u64 v[144:145], s[58:59], 0, v[130:131]
	s_mov_b32 m0, s54
	ds_read_b128 v[188:191], v151 offset:16384
	ds_read_b128 v[192:195], v151 offset:17408
	ds_read_b128 v[196:199], v151 offset:18432
	ds_read_b128 v[200:203], v151 offset:19456
	ds_read_b128 v[204:207], v151 offset:20480
	ds_read_b128 v[208:211], v151 offset:21504
	ds_read_b128 v[212:215], v151 offset:22528
	ds_read_b128 v[216:219], v151 offset:23552
	global_load_lds_dwordx4 v[144:145], off
	s_add_i32 m0, s54, 0x2000
	s_add_u32 s54, s58, 0xb0000
	v_lshl_add_u64 v[220:221], s[58:59], 0, v[134:135]
	s_addc_u32 s55, s59, 0
	s_add_i32 s79, s73, s64
	global_load_lds_dwordx4 v[220:221], off
	v_lshl_add_u64 v[222:223], s[54:55], 0, v[130:131]
	s_mov_b32 m0, s79
	v_lshl_add_u64 v[224:225], s[60:61], 0, v[132:133]
	global_load_lds_dwordx4 v[222:223], off
	v_lshl_add_u64 v[222:223], s[54:55], 0, v[134:135]
	s_add_i32 m0, s79, 0x2000
	s_nop 0
	global_load_lds_dwordx4 v[222:223], off
	v_lshl_add_u64 v[222:223], s[60:61], 0, v[128:129]
	s_mov_b32 m0, s65
	s_nop 0
	global_load_lds_dwordx4 v[222:223], off nt
	s_mov_b32 m0, s66
	s_nop 0
	global_load_lds_dwordx4 v[224:225], off nt
	s_waitcnt vmcnt(8)
	s_waitcnt lgkmcnt(0)
	s_barrier
	s_setprio 1
	s_waitcnt lgkmcnt(0)
	v_mfma_f32_16x16x32_bf16 v[60:63], v[152:155], v[188:191], v[60:63]
	v_mfma_f32_16x16x32_bf16 v[60:63], v[156:159], v[192:195], v[60:63]
	v_mfma_f32_16x16x32_bf16 v[56:59], v[160:163], v[188:191], v[56:59]
	v_mfma_f32_16x16x32_bf16 v[56:59], v[164:167], v[192:195], v[56:59]
	v_mfma_f32_16x16x32_bf16 v[52:55], v[152:155], v[196:199], v[52:55]
	v_mfma_f32_16x16x32_bf16 v[52:55], v[156:159], v[200:203], v[52:55]
	v_mfma_f32_16x16x32_bf16 v[44:47], v[160:163], v[196:199], v[44:47]
	v_mfma_f32_16x16x32_bf16 v[44:47], v[164:167], v[200:203], v[44:47]
	v_mfma_f32_16x16x32_bf16 v[36:39], v[152:155], v[204:207], v[36:39]
	v_mfma_f32_16x16x32_bf16 v[36:39], v[156:159], v[208:211], v[36:39]
	v_mfma_f32_16x16x32_bf16 v[28:31], v[160:163], v[204:207], v[28:31]
	v_mfma_f32_16x16x32_bf16 v[28:31], v[164:167], v[208:211], v[28:31]
	v_mfma_f32_16x16x32_bf16 v[20:23], v[152:155], v[212:215], v[20:23]
	v_mfma_f32_16x16x32_bf16 v[20:23], v[156:159], v[216:219], v[20:23]
	v_mfma_f32_16x16x32_bf16 v[12:15], v[160:163], v[212:215], v[12:15]
	v_mfma_f32_16x16x32_bf16 v[12:15], v[164:167], v[216:219], v[12:15]
	v_mfma_f32_16x16x32_bf16 v[48:51], v[168:171], v[188:191], v[48:51]
	v_mfma_f32_16x16x32_bf16 v[48:51], v[172:175], v[192:195], v[48:51]
	v_mfma_f32_16x16x32_bf16 v[40:43], v[176:179], v[188:191], v[40:43]
	v_mfma_f32_16x16x32_bf16 v[40:43], v[184:187], v[192:195], v[40:43]
	v_mfma_f32_16x16x32_bf16 v[32:35], v[168:171], v[196:199], v[32:35]
	v_mfma_f32_16x16x32_bf16 v[32:35], v[172:175], v[200:203], v[32:35]
	v_mfma_f32_16x16x32_bf16 v[24:27], v[176:179], v[196:199], v[24:27]
	v_mfma_f32_16x16x32_bf16 v[24:27], v[184:187], v[200:203], v[24:27]
	v_mfma_f32_16x16x32_bf16 v[16:19], v[168:171], v[204:207], v[16:19]
	v_mfma_f32_16x16x32_bf16 v[16:19], v[172:175], v[208:211], v[16:19]
	v_mfma_f32_16x16x32_bf16 v[8:11], v[176:179], v[204:207], v[8:11]
	v_mfma_f32_16x16x32_bf16 v[8:11], v[184:187], v[208:211], v[8:11]
	v_mfma_f32_16x16x32_bf16 v[4:7], v[168:171], v[212:215], v[4:7]
	v_mfma_f32_16x16x32_bf16 v[4:7], v[172:175], v[216:219], v[4:7]
	v_mfma_f32_16x16x32_bf16 v[0:3], v[176:179], v[212:215], v[0:3]
	v_mfma_f32_16x16x32_bf16 v[0:3], v[184:187], v[216:219], v[0:3]
	s_setprio 0
	s_barrier
.Lmid_gemm8:
	s_add_i32 s79, 0, 0x18000
	s_add_i32 s89, 0, 0x1c000
	v_add_u32_e32 v164, s79, v147
	v_add_u32_e32 v181, s89, v147
	ds_read_b128 v[152:155], v164
	ds_read_b128 v[156:159], v164 offset:1024
	ds_read_b128 v[160:163], v164 offset:2048
	ds_read_b128 v[164:167], v164 offset:3072
	ds_read_b128 v[168:171], v181
	ds_read_b128 v[172:175], v181 offset:1024
	ds_read_b128 v[176:179], v181 offset:2048
	ds_read_b128 v[184:187], v181 offset:3072
	s_add_u32 s54, s60, 0xb0000
	s_addc_u32 s55, s61, 0
	s_mov_b32 m0, s67
	v_lshl_add_u64 v[226:227], s[54:55], 0, v[128:129]
	ds_read_b128 v[188:191], v151 offset:32768
	ds_read_b128 v[192:195], v151 offset:33792
	ds_read_b128 v[196:199], v151 offset:34816
	ds_read_b128 v[200:203], v151 offset:35840
	ds_read_b128 v[204:207], v151 offset:36864
	ds_read_b128 v[208:211], v151 offset:37888
	ds_read_b128 v[212:215], v151 offset:38912
	ds_read_b128 v[216:219], v151 offset:39936
	global_load_lds_dwordx4 v[226:227], off nt
	v_lshl_add_u64 v[226:227], s[54:55], 0, v[132:133]
	s_mov_b32 m0, s68
	s_nop 0
	global_load_lds_dwordx4 v[226:227], off nt
	s_waitcnt vmcnt(8)
	s_waitcnt lgkmcnt(0)
	s_barrier
	s_setprio 1
	s_waitcnt lgkmcnt(0)
	v_mfma_f32_16x16x32_bf16 v[124:127], v[152:155], v[188:191], v[124:127]
	v_mfma_f32_16x16x32_bf16 v[124:127], v[156:159], v[192:195], v[124:127]
	v_mfma_f32_16x16x32_bf16 v[120:123], v[160:163], v[188:191], v[120:123]
	v_mfma_f32_16x16x32_bf16 v[120:123], v[164:167], v[192:195], v[120:123]
	v_mfma_f32_16x16x32_bf16 v[116:119], v[152:155], v[196:199], v[116:119]
	v_mfma_f32_16x16x32_bf16 v[116:119], v[156:159], v[200:203], v[116:119]
	v_mfma_f32_16x16x32_bf16 v[108:111], v[160:163], v[196:199], v[108:111]
	v_mfma_f32_16x16x32_bf16 v[108:111], v[164:167], v[200:203], v[108:111]
	v_mfma_f32_16x16x32_bf16 v[100:103], v[152:155], v[204:207], v[100:103]
	v_mfma_f32_16x16x32_bf16 v[100:103], v[156:159], v[208:211], v[100:103]
	v_mfma_f32_16x16x32_bf16 v[92:95], v[160:163], v[204:207], v[92:95]
	v_mfma_f32_16x16x32_bf16 v[92:95], v[164:167], v[208:211], v[92:95]
	v_mfma_f32_16x16x32_bf16 v[84:87], v[152:155], v[212:215], v[84:87]
	v_mfma_f32_16x16x32_bf16 v[84:87], v[156:159], v[216:219], v[84:87]
	v_mfma_f32_16x16x32_bf16 v[76:79], v[160:163], v[212:215], v[76:79]
	v_mfma_f32_16x16x32_bf16 v[76:79], v[164:167], v[216:219], v[76:79]
	v_mfma_f32_16x16x32_bf16 v[112:115], v[168:171], v[188:191], v[112:115]
	v_mfma_f32_16x16x32_bf16 v[112:115], v[172:175], v[192:195], v[112:115]
	v_mfma_f32_16x16x32_bf16 v[104:107], v[176:179], v[188:191], v[104:107]
	v_mfma_f32_16x16x32_bf16 v[104:107], v[184:187], v[192:195], v[104:107]
	v_mfma_f32_16x16x32_bf16 v[96:99], v[168:171], v[196:199], v[96:99]
	v_mfma_f32_16x16x32_bf16 v[96:99], v[172:175], v[200:203], v[96:99]
	v_mfma_f32_16x16x32_bf16 v[88:91], v[176:179], v[196:199], v[88:91]
	v_mfma_f32_16x16x32_bf16 v[88:91], v[184:187], v[200:203], v[88:91]
	v_mfma_f32_16x16x32_bf16 v[80:83], v[168:171], v[204:207], v[80:83]
	v_mfma_f32_16x16x32_bf16 v[80:83], v[172:175], v[208:211], v[80:83]
	v_mfma_f32_16x16x32_bf16 v[72:75], v[176:179], v[204:207], v[72:75]
	v_mfma_f32_16x16x32_bf16 v[72:75], v[184:187], v[208:211], v[72:75]
	v_mfma_f32_16x16x32_bf16 v[68:71], v[168:171], v[212:215], v[68:71]
	v_mfma_f32_16x16x32_bf16 v[68:71], v[172:175], v[216:219], v[68:71]
	v_mfma_f32_16x16x32_bf16 v[64:67], v[176:179], v[212:215], v[64:67]
	v_mfma_f32_16x16x32_bf16 v[64:67], v[184:187], v[216:219], v[64:67]
	s_setprio 0
	s_barrier
	s_add_i32 s54, s79, s64
	v_lshl_add_u64 v[144:145], v[144:145], 0, s[16:17]
	s_mov_b32 m0, s54
	ds_read_b128 v[188:191], v151 offset:49152
	ds_read_b128 v[192:195], v151 offset:50176
	ds_read_b128 v[196:199], v151 offset:51200
	ds_read_b128 v[200:203], v151 offset:52224
	ds_read_b128 v[204:207], v151 offset:53248
	ds_read_b128 v[208:211], v151 offset:54272
	ds_read_b128 v[212:215], v151 offset:55296
	ds_read_b128 v[216:219], v151 offset:56320
	global_load_lds_dwordx4 v[144:145], off
	s_add_i32 m0, s54, 0x2000
	s_add_u32 s54, s58, 0xb0080
	v_lshl_add_u64 v[144:145], v[220:221], 0, s[16:17]
	s_addc_u32 s55, s59, 0
	s_add_i32 s58, s89, s64
	global_load_lds_dwordx4 v[144:145], off
	v_lshl_add_u64 v[144:145], s[54:55], 0, v[130:131]
	s_mov_b32 m0, s58
	s_nop 0
	global_load_lds_dwordx4 v[144:145], off
	v_lshl_add_u64 v[144:145], s[54:55], 0, v[134:135]
	s_add_i32 m0, s58, 0x2000
	s_nop 0
	global_load_lds_dwordx4 v[144:145], off
	v_lshl_add_u64 v[144:145], v[222:223], 0, s[16:17]
	s_mov_b32 m0, s70
	s_nop 0
	global_load_lds_dwordx4 v[144:145], off nt
	v_lshl_add_u64 v[144:145], v[224:225], 0, s[16:17]
	s_mov_b32 m0, s71
	s_nop 0
	global_load_lds_dwordx4 v[144:145], off nt
	s_waitcnt vmcnt(8)
	s_waitcnt lgkmcnt(0)
	s_barrier
	s_setprio 1
	s_waitcnt lgkmcnt(0)
	v_mfma_f32_16x16x32_bf16 v[60:63], v[152:155], v[188:191], v[60:63]
	v_mfma_f32_16x16x32_bf16 v[60:63], v[156:159], v[192:195], v[60:63]
	v_mfma_f32_16x16x32_bf16 v[56:59], v[160:163], v[188:191], v[56:59]
	v_mfma_f32_16x16x32_bf16 v[56:59], v[164:167], v[192:195], v[56:59]
	v_mfma_f32_16x16x32_bf16 v[52:55], v[152:155], v[196:199], v[52:55]
	v_mfma_f32_16x16x32_bf16 v[52:55], v[156:159], v[200:203], v[52:55]
	v_mfma_f32_16x16x32_bf16 v[44:47], v[160:163], v[196:199], v[44:47]
	v_mfma_f32_16x16x32_bf16 v[44:47], v[164:167], v[200:203], v[44:47]
	v_mfma_f32_16x16x32_bf16 v[36:39], v[152:155], v[204:207], v[36:39]
	v_mfma_f32_16x16x32_bf16 v[36:39], v[156:159], v[208:211], v[36:39]
	v_mfma_f32_16x16x32_bf16 v[28:31], v[160:163], v[204:207], v[28:31]
	v_mfma_f32_16x16x32_bf16 v[28:31], v[164:167], v[208:211], v[28:31]
	v_mfma_f32_16x16x32_bf16 v[20:23], v[152:155], v[212:215], v[20:23]
	v_mfma_f32_16x16x32_bf16 v[20:23], v[156:159], v[216:219], v[20:23]
	v_mfma_f32_16x16x32_bf16 v[12:15], v[160:163], v[212:215], v[12:15]
	v_mfma_f32_16x16x32_bf16 v[12:15], v[164:167], v[216:219], v[12:15]
	v_mfma_f32_16x16x32_bf16 v[48:51], v[168:171], v[188:191], v[48:51]
	v_mfma_f32_16x16x32_bf16 v[48:51], v[172:175], v[192:195], v[48:51]
	v_mfma_f32_16x16x32_bf16 v[40:43], v[176:179], v[188:191], v[40:43]
	v_mfma_f32_16x16x32_bf16 v[40:43], v[184:187], v[192:195], v[40:43]
	v_mfma_f32_16x16x32_bf16 v[32:35], v[168:171], v[196:199], v[32:35]
	v_mfma_f32_16x16x32_bf16 v[32:35], v[172:175], v[200:203], v[32:35]
	v_mfma_f32_16x16x32_bf16 v[24:27], v[176:179], v[196:199], v[24:27]
	v_mfma_f32_16x16x32_bf16 v[24:27], v[184:187], v[200:203], v[24:27]
	v_mfma_f32_16x16x32_bf16 v[16:19], v[168:171], v[204:207], v[16:19]
	v_mfma_f32_16x16x32_bf16 v[16:19], v[172:175], v[208:211], v[16:19]
	v_mfma_f32_16x16x32_bf16 v[8:11], v[176:179], v[204:207], v[8:11]
	v_mfma_f32_16x16x32_bf16 v[8:11], v[184:187], v[208:211], v[8:11]
	v_mfma_f32_16x16x32_bf16 v[4:7], v[168:171], v[212:215], v[4:7]
	v_mfma_f32_16x16x32_bf16 v[4:7], v[172:175], v[216:219], v[4:7]
	v_mfma_f32_16x16x32_bf16 v[0:3], v[176:179], v[212:215], v[0:3]
	v_mfma_f32_16x16x32_bf16 v[0:3], v[184:187], v[216:219], v[0:3]
	s_setprio 0
	s_barrier
	s_add_i32 s88, s88, 2
	s_add_u32 s86, s86, 0x100
	s_addc_u32 s87, s87, 0
	s_cmp_gt_u32 s88, 41
	s_mov_b64 s[54:55], s[56:57]
	s_cbranch_scc0 .LBB0_1031
	s_and_b64 vcc, exec, s[18:19]
	s_cbranch_vccz .LBB0_1034
	s_barrier

.LBB0_1513:
	s_add_u32 s74, s48, 0x100
	s_addc_u32 s75, s49, 0
	s_mov_b32 s76, -2
	ds_read_b128 v[152:155], v149
	ds_read_b128 v[156:159], v149 offset:1024
	ds_read_b128 v[160:163], v149 offset:2048
	ds_read_b128 v[164:167], v149 offset:3072
	ds_read_b128 v[168:171], v150
	ds_read_b128 v[172:175], v150 offset:1024
	ds_read_b128 v[176:179], v150 offset:2048
	ds_read_b128 v[184:187], v150 offset:3072
	s_add_u32 s48, s46, 0x100
	s_addc_u32 s49, s47, 0
	s_cmp_eq_u32 s76, 40
	s_cselect_b32 s53, s9, s49
	s_cselect_b32 s52, s8, s48
	s_cselect_b32 s51, s45, s75
	s_cselect_b32 s50, s44, s74
	v_lshl_add_u64 v[144:145], s[46:47], 0, v[136:137]
	s_add_i32 m0, s57, 0xc000
	ds_read_b128 v[188:191], v151
	ds_read_b128 v[192:195], v151 offset:1024
	ds_read_b128 v[196:199], v151 offset:2048
	ds_read_b128 v[200:203], v151 offset:3072
	ds_read_b128 v[204:207], v151 offset:4096
	ds_read_b128 v[208:211], v151 offset:5120
	ds_read_b128 v[212:215], v151 offset:6144
	ds_read_b128 v[216:219], v151 offset:7168
	global_load_lds_dwordx4 v[144:145], off nt
	v_lshl_add_u64 v[144:145], s[46:47], 0, v[138:139]
	s_add_i32 m0, s57, 0xe000
	s_nop 0
	global_load_lds_dwordx4 v[144:145], off nt
	s_waitcnt vmcnt(8)
	s_waitcnt lgkmcnt(0)
	s_barrier
	s_setprio 1
	s_waitcnt lgkmcnt(0)
	v_mfma_f32_16x16x32_bf16 v[124:127], v[152:155], v[188:191], 0
	v_mfma_f32_16x16x32_bf16 v[124:127], v[156:159], v[192:195], v[124:127]
	v_mfma_f32_16x16x32_bf16 v[120:123], v[160:163], v[188:191], 0
	v_mfma_f32_16x16x32_bf16 v[120:123], v[164:167], v[192:195], v[120:123]
	v_mfma_f32_16x16x32_bf16 v[116:119], v[152:155], v[196:199], 0
	v_mfma_f32_16x16x32_bf16 v[116:119], v[156:159], v[200:203], v[116:119]
	v_mfma_f32_16x16x32_bf16 v[108:111], v[160:163], v[196:199], 0
	v_mfma_f32_16x16x32_bf16 v[108:111], v[164:167], v[200:203], v[108:111]
	v_mfma_f32_16x16x32_bf16 v[100:103], v[152:155], v[204:207], 0
	v_mfma_f32_16x16x32_bf16 v[100:103], v[156:159], v[208:211], v[100:103]
	v_mfma_f32_16x16x32_bf16 v[92:95], v[160:163], v[204:207], 0
	v_mfma_f32_16x16x32_bf16 v[92:95], v[164:167], v[208:211], v[92:95]
	v_mfma_f32_16x16x32_bf16 v[84:87], v[152:155], v[212:215], 0
	v_mfma_f32_16x16x32_bf16 v[84:87], v[156:159], v[216:219], v[84:87]
	v_mfma_f32_16x16x32_bf16 v[76:79], v[160:163], v[212:215], 0
	v_mfma_f32_16x16x32_bf16 v[76:79], v[164:167], v[216:219], v[76:79]
	v_mfma_f32_16x16x32_bf16 v[112:115], v[168:171], v[188:191], 0
	v_mfma_f32_16x16x32_bf16 v[112:115], v[172:175], v[192:195], v[112:115]
	v_mfma_f32_16x16x32_bf16 v[104:107], v[176:179], v[188:191], 0
	v_mfma_f32_16x16x32_bf16 v[104:107], v[184:187], v[192:195], v[104:107]
	v_mfma_f32_16x16x32_bf16 v[96:99], v[168:171], v[196:199], 0
	v_mfma_f32_16x16x32_bf16 v[96:99], v[172:175], v[200:203], v[96:99]
	v_mfma_f32_16x16x32_bf16 v[88:91], v[176:179], v[196:199], 0
	v_mfma_f32_16x16x32_bf16 v[88:91], v[184:187], v[200:203], v[88:91]
	v_mfma_f32_16x16x32_bf16 v[80:83], v[168:171], v[204:207], 0
	v_mfma_f32_16x16x32_bf16 v[80:83], v[172:175], v[208:211], v[80:83]
	v_mfma_f32_16x16x32_bf16 v[72:75], v[176:179], v[204:207], 0
	v_mfma_f32_16x16x32_bf16 v[72:75], v[184:187], v[208:211], v[72:75]
	v_mfma_f32_16x16x32_bf16 v[68:71], v[168:171], v[212:215], 0
	v_mfma_f32_16x16x32_bf16 v[68:71], v[172:175], v[216:219], v[68:71]
	v_mfma_f32_16x16x32_bf16 v[64:67], v[176:179], v[212:215], 0
	v_mfma_f32_16x16x32_bf16 v[64:67], v[184:187], v[216:219], v[64:67]
	s_setprio 0
	s_barrier
	s_add_i32 s46, s64, s56
	v_lshl_add_u64 v[144:145], s[50:51], 0, v[130:131]
	s_mov_b32 m0, s46
	ds_read_b128 v[188:191], v151 offset:16384
	ds_read_b128 v[192:195], v151 offset:17408
	ds_read_b128 v[196:199], v151 offset:18432
	ds_read_b128 v[200:203], v151 offset:19456
	ds_read_b128 v[204:207], v151 offset:20480
	ds_read_b128 v[208:211], v151 offset:21504
	ds_read_b128 v[212:215], v151 offset:22528
	ds_read_b128 v[216:219], v151 offset:23552
	global_load_lds_dwordx4 v[144:145], off
	s_add_i32 m0, s46, 0x2000
	s_add_u32 s46, s50, 0xb0000
	v_lshl_add_u64 v[220:221], s[50:51], 0, v[134:135]
	s_addc_u32 s47, s51, 0
	s_add_i32 s77, s65, s56
	global_load_lds_dwordx4 v[220:221], off
	v_lshl_add_u64 v[222:223], s[46:47], 0, v[130:131]
	s_mov_b32 m0, s77
	v_lshl_add_u64 v[224:225], s[52:53], 0, v[132:133]
	global_load_lds_dwordx4 v[222:223], off
	v_lshl_add_u64 v[222:223], s[46:47], 0, v[134:135]
	s_add_i32 m0, s77, 0x2000
	s_nop 0
	global_load_lds_dwordx4 v[222:223], off
	v_lshl_add_u64 v[222:223], s[52:53], 0, v[128:129]
	s_mov_b32 m0, s57
	s_nop 0
	global_load_lds_dwordx4 v[222:223], off nt
	s_mov_b32 m0, s58
	s_nop 0
	global_load_lds_dwordx4 v[224:225], off nt
	s_waitcnt vmcnt(8)
	s_waitcnt lgkmcnt(0)
	s_barrier
	s_setprio 1
	s_waitcnt lgkmcnt(0)
	v_mfma_f32_16x16x32_bf16 v[60:63], v[152:155], v[188:191], 0
	v_mfma_f32_16x16x32_bf16 v[60:63], v[156:159], v[192:195], v[60:63]
	v_mfma_f32_16x16x32_bf16 v[56:59], v[160:163], v[188:191], 0
	v_mfma_f32_16x16x32_bf16 v[56:59], v[164:167], v[192:195], v[56:59]
	v_mfma_f32_16x16x32_bf16 v[52:55], v[152:155], v[196:199], 0
	v_mfma_f32_16x16x32_bf16 v[52:55], v[156:159], v[200:203], v[52:55]
	v_mfma_f32_16x16x32_bf16 v[44:47], v[160:163], v[196:199], 0
	v_mfma_f32_16x16x32_bf16 v[44:47], v[164:167], v[200:203], v[44:47]
	v_mfma_f32_16x16x32_bf16 v[36:39], v[152:155], v[204:207], 0
	v_mfma_f32_16x16x32_bf16 v[36:39], v[156:159], v[208:211], v[36:39]
	v_mfma_f32_16x16x32_bf16 v[28:31], v[160:163], v[204:207], 0
	v_mfma_f32_16x16x32_bf16 v[28:31], v[164:167], v[208:211], v[28:31]
	v_mfma_f32_16x16x32_bf16 v[20:23], v[152:155], v[212:215], 0
	v_mfma_f32_16x16x32_bf16 v[20:23], v[156:159], v[216:219], v[20:23]
	v_mfma_f32_16x16x32_bf16 v[12:15], v[160:163], v[212:215], 0
	v_mfma_f32_16x16x32_bf16 v[12:15], v[164:167], v[216:219], v[12:15]
	v_mfma_f32_16x16x32_bf16 v[48:51], v[168:171], v[188:191], 0
	v_mfma_f32_16x16x32_bf16 v[48:51], v[172:175], v[192:195], v[48:51]
	v_mfma_f32_16x16x32_bf16 v[40:43], v[176:179], v[188:191], 0
	v_mfma_f32_16x16x32_bf16 v[40:43], v[184:187], v[192:195], v[40:43]
	v_mfma_f32_16x16x32_bf16 v[32:35], v[168:171], v[196:199], 0
	v_mfma_f32_16x16x32_bf16 v[32:35], v[172:175], v[200:203], v[32:35]
	v_mfma_f32_16x16x32_bf16 v[24:27], v[176:179], v[196:199], 0
	v_mfma_f32_16x16x32_bf16 v[24:27], v[184:187], v[200:203], v[24:27]
	v_mfma_f32_16x16x32_bf16 v[16:19], v[168:171], v[204:207], 0
	v_mfma_f32_16x16x32_bf16 v[16:19], v[172:175], v[208:211], v[16:19]
	v_mfma_f32_16x16x32_bf16 v[8:11], v[176:179], v[204:207], 0
	v_mfma_f32_16x16x32_bf16 v[8:11], v[184:187], v[208:211], v[8:11]
	v_mfma_f32_16x16x32_bf16 v[4:7], v[168:171], v[212:215], 0
	v_mfma_f32_16x16x32_bf16 v[4:7], v[172:175], v[216:219], v[4:7]
	v_mfma_f32_16x16x32_bf16 v[0:3], v[176:179], v[212:215], 0
	v_mfma_f32_16x16x32_bf16 v[0:3], v[184:187], v[216:219], v[0:3]
	s_setprio 0
	s_barrier
	s_branch .Lmid_gemm12
.LBB0_1514:
	ds_read_b128 v[152:155], v149
	ds_read_b128 v[156:159], v149 offset:1024
	ds_read_b128 v[160:163], v149 offset:2048
	ds_read_b128 v[164:167], v149 offset:3072
	ds_read_b128 v[168:171], v150
	ds_read_b128 v[172:175], v150 offset:1024
	ds_read_b128 v[176:179], v150 offset:2048
	ds_read_b128 v[184:187], v150 offset:3072
	s_add_u32 s48, s46, 0x100
	s_addc_u32 s49, s47, 0
	s_cmp_eq_u32 s76, 40
	s_cselect_b32 s53, s9, s49
	s_cselect_b32 s52, s8, s48
	s_cselect_b32 s51, s45, s75
	s_cselect_b32 s50, s44, s74
	v_lshl_add_u64 v[144:145], s[46:47], 0, v[136:137]
	s_add_i32 m0, s57, 0xc000
	ds_read_b128 v[188:191], v151
	ds_read_b128 v[192:195], v151 offset:1024
	ds_read_b128 v[196:199], v151 offset:2048
	ds_read_b128 v[200:203], v151 offset:3072
	ds_read_b128 v[204:207], v151 offset:4096
	ds_read_b128 v[208:211], v151 offset:5120
	ds_read_b128 v[212:215], v151 offset:6144
	ds_read_b128 v[216:219], v151 offset:7168
	global_load_lds_dwordx4 v[144:145], off nt
	v_lshl_add_u64 v[144:145], s[46:47], 0, v[138:139]
	s_add_i32 m0, s57, 0xe000
	s_nop 0
	global_load_lds_dwordx4 v[144:145], off nt
	s_waitcnt vmcnt(8)
	s_waitcnt lgkmcnt(0)
	s_barrier
	s_setprio 1
	s_waitcnt lgkmcnt(0)
	v_mfma_f32_16x16x32_bf16 v[124:127], v[152:155], v[188:191], v[124:127]
	v_mfma_f32_16x16x32_bf16 v[124:127], v[156:159], v[192:195], v[124:127]
	v_mfma_f32_16x16x32_bf16 v[120:123], v[160:163], v[188:191], v[120:123]
	v_mfma_f32_16x16x32_bf16 v[120:123], v[164:167], v[192:195], v[120:123]
	v_mfma_f32_16x16x32_bf16 v[116:119], v[152:155], v[196:199], v[116:119]
	v_mfma_f32_16x16x32_bf16 v[116:119], v[156:159], v[200:203], v[116:119]
	v_mfma_f32_16x16x32_bf16 v[108:111], v[160:163], v[196:199], v[108:111]
	v_mfma_f32_16x16x32_bf16 v[108:111], v[164:167], v[200:203], v[108:111]
	v_mfma_f32_16x16x32_bf16 v[100:103], v[152:155], v[204:207], v[100:103]
	v_mfma_f32_16x16x32_bf16 v[100:103], v[156:159], v[208:211], v[100:103]
	v_mfma_f32_16x16x32_bf16 v[92:95], v[160:163], v[204:207], v[92:95]
	v_mfma_f32_16x16x32_bf16 v[92:95], v[164:167], v[208:211], v[92:95]
	v_mfma_f32_16x16x32_bf16 v[84:87], v[152:155], v[212:215], v[84:87]
	v_mfma_f32_16x16x32_bf16 v[84:87], v[156:159], v[216:219], v[84:87]
	v_mfma_f32_16x16x32_bf16 v[76:79], v[160:163], v[212:215], v[76:79]
	v_mfma_f32_16x16x32_bf16 v[76:79], v[164:167], v[216:219], v[76:79]
	v_mfma_f32_16x16x32_bf16 v[112:115], v[168:171], v[188:191], v[112:115]
	v_mfma_f32_16x16x32_bf16 v[112:115], v[172:175], v[192:195], v[112:115]
	v_mfma_f32_16x16x32_bf16 v[104:107], v[176:179], v[188:191], v[104:107]
	v_mfma_f32_16x16x32_bf16 v[104:107], v[184:187], v[192:195], v[104:107]
	v_mfma_f32_16x16x32_bf16 v[96:99], v[168:171], v[196:199], v[96:99]
	v_mfma_f32_16x16x32_bf16 v[96:99], v[172:175], v[200:203], v[96:99]
	v_mfma_f32_16x16x32_bf16 v[88:91], v[176:179], v[196:199], v[88:91]
	v_mfma_f32_16x16x32_bf16 v[88:91], v[184:187], v[200:203], v[88:91]
	v_mfma_f32_16x16x32_bf16 v[80:83], v[168:171], v[204:207], v[80:83]
	v_mfma_f32_16x16x32_bf16 v[80:83], v[172:175], v[208:211], v[80:83]
	v_mfma_f32_16x16x32_bf16 v[72:75], v[176:179], v[204:207], v[72:75]
	v_mfma_f32_16x16x32_bf16 v[72:75], v[184:187], v[208:211], v[72:75]
	v_mfma_f32_16x16x32_bf16 v[68:71], v[168:171], v[212:215], v[68:71]
	v_mfma_f32_16x16x32_bf16 v[68:71], v[172:175], v[216:219], v[68:71]
	v_mfma_f32_16x16x32_bf16 v[64:67], v[176:179], v[212:215], v[64:67]
	v_mfma_f32_16x16x32_bf16 v[64:67], v[184:187], v[216:219], v[64:67]
	s_setprio 0
	s_barrier
	s_add_i32 s46, s64, s56
	v_lshl_add_u64 v[144:145], s[50:51], 0, v[130:131]
	s_mov_b32 m0, s46
	ds_read_b128 v[188:191], v151 offset:16384
	ds_read_b128 v[192:195], v151 offset:17408
	ds_read_b128 v[196:199], v151 offset:18432
	ds_read_b128 v[200:203], v151 offset:19456
	ds_read_b128 v[204:207], v151 offset:20480
	ds_read_b128 v[208:211], v151 offset:21504
	ds_read_b128 v[212:215], v151 offset:22528
	ds_read_b128 v[216:219], v151 offset:23552
	global_load_lds_dwordx4 v[144:145], off
	s_add_i32 m0, s46, 0x2000
	s_add_u32 s46, s50, 0xb0000
	v_lshl_add_u64 v[220:221], s[50:51], 0, v[134:135]
	s_addc_u32 s47, s51, 0
	s_add_i32 s77, s65, s56
	global_load_lds_dwordx4 v[220:221], off
	v_lshl_add_u64 v[222:223], s[46:47], 0, v[130:131]
	s_mov_b32 m0, s77
	v_lshl_add_u64 v[224:225], s[52:53], 0, v[132:133]
	global_load_lds_dwordx4 v[222:223], off
	v_lshl_add_u64 v[222:223], s[46:47], 0, v[134:135]
	s_add_i32 m0, s77, 0x2000
	s_nop 0
	global_load_lds_dwordx4 v[222:223], off
	v_lshl_add_u64 v[222:223], s[52:53], 0, v[128:129]
	s_mov_b32 m0, s57
	s_nop 0
	global_load_lds_dwordx4 v[222:223], off nt
	s_mov_b32 m0, s58
	s_nop 0
	global_load_lds_dwordx4 v[224:225], off nt
	s_waitcnt vmcnt(8)
	s_waitcnt lgkmcnt(0)
	s_barrier
	s_setprio 1
	s_waitcnt lgkmcnt(0)
	v_mfma_f32_16x16x32_bf16 v[60:63], v[152:155], v[188:191], v[60:63]
	v_mfma_f32_16x16x32_bf16 v[60:63], v[156:159], v[192:195], v[60:63]
	v_mfma_f32_16x16x32_bf16 v[56:59], v[160:163], v[188:191], v[56:59]
	v_mfma_f32_16x16x32_bf16 v[56:59], v[164:167], v[192:195], v[56:59]
	v_mfma_f32_16x16x32_bf16 v[52:55], v[152:155], v[196:199], v[52:55]
	v_mfma_f32_16x16x32_bf16 v[52:55], v[156:159], v[200:203], v[52:55]
	v_mfma_f32_16x16x32_bf16 v[44:47], v[160:163], v[196:199], v[44:47]
	v_mfma_f32_16x16x32_bf16 v[44:47], v[164:167], v[200:203], v[44:47]
	v_mfma_f32_16x16x32_bf16 v[36:39], v[152:155], v[204:207], v[36:39]
	v_mfma_f32_16x16x32_bf16 v[36:39], v[156:159], v[208:211], v[36:39]
	v_mfma_f32_16x16x32_bf16 v[28:31], v[160:163], v[204:207], v[28:31]
	v_mfma_f32_16x16x32_bf16 v[28:31], v[164:167], v[208:211], v[28:31]
	v_mfma_f32_16x16x32_bf16 v[20:23], v[152:155], v[212:215], v[20:23]
	v_mfma_f32_16x16x32_bf16 v[20:23], v[156:159], v[216:219], v[20:23]
	v_mfma_f32_16x16x32_bf16 v[12:15], v[160:163], v[212:215], v[12:15]
	v_mfma_f32_16x16x32_bf16 v[12:15], v[164:167], v[216:219], v[12:15]
	v_mfma_f32_16x16x32_bf16 v[48:51], v[168:171], v[188:191], v[48:51]
	v_mfma_f32_16x16x32_bf16 v[48:51], v[172:175], v[192:195], v[48:51]
	v_mfma_f32_16x16x32_bf16 v[40:43], v[176:179], v[188:191], v[40:43]
	v_mfma_f32_16x16x32_bf16 v[40:43], v[184:187], v[192:195], v[40:43]
	v_mfma_f32_16x16x32_bf16 v[32:35], v[168:171], v[196:199], v[32:35]
	v_mfma_f32_16x16x32_bf16 v[32:35], v[172:175], v[200:203], v[32:35]
	v_mfma_f32_16x16x32_bf16 v[24:27], v[176:179], v[196:199], v[24:27]
	v_mfma_f32_16x16x32_bf16 v[24:27], v[184:187], v[200:203], v[24:27]
	v_mfma_f32_16x16x32_bf16 v[16:19], v[168:171], v[204:207], v[16:19]
	v_mfma_f32_16x16x32_bf16 v[16:19], v[172:175], v[208:211], v[16:19]
	v_mfma_f32_16x16x32_bf16 v[8:11], v[176:179], v[204:207], v[8:11]
	v_mfma_f32_16x16x32_bf16 v[8:11], v[184:187], v[208:211], v[8:11]
	v_mfma_f32_16x16x32_bf16 v[4:7], v[168:171], v[212:215], v[4:7]
	v_mfma_f32_16x16x32_bf16 v[4:7], v[172:175], v[216:219], v[4:7]
	v_mfma_f32_16x16x32_bf16 v[0:3], v[176:179], v[212:215], v[0:3]
	v_mfma_f32_16x16x32_bf16 v[0:3], v[184:187], v[216:219], v[0:3]
	s_setprio 0
	s_barrier
.Lmid_gemm12:
	s_add_i32 s77, 0, 0x18000
	s_add_i32 s79, 0, 0x1c000
	v_add_u32_e32 v164, s77, v147
	v_add_u32_e32 v181, s79, v147
	ds_read_b128 v[152:155], v164
	ds_read_b128 v[156:159], v164 offset:1024
	ds_read_b128 v[160:163], v164 offset:2048
	ds_read_b128 v[164:167], v164 offset:3072
	ds_read_b128 v[168:171], v181
	ds_read_b128 v[172:175], v181 offset:1024
	ds_read_b128 v[176:179], v181 offset:2048
	ds_read_b128 v[184:187], v181 offset:3072
	s_add_u32 s46, s52, 0xb0000
	s_addc_u32 s47, s53, 0
	s_mov_b32 m0, s59
	v_lshl_add_u64 v[226:227], s[46:47], 0, v[128:129]
	ds_read_b128 v[188:191], v151 offset:32768
	ds_read_b128 v[192:195], v151 offset:33792
	ds_read_b128 v[196:199], v151 offset:34816
	ds_read_b128 v[200:203], v151 offset:35840
	ds_read_b128 v[204:207], v151 offset:36864
	ds_read_b128 v[208:211], v151 offset:37888
	ds_read_b128 v[212:215], v151 offset:38912
	ds_read_b128 v[216:219], v151 offset:39936
	global_load_lds_dwordx4 v[226:227], off nt
	v_lshl_add_u64 v[226:227], s[46:47], 0, v[132:133]
	s_mov_b32 m0, s60
	s_nop 0
	global_load_lds_dwordx4 v[226:227], off nt
	s_waitcnt vmcnt(8)
	s_waitcnt lgkmcnt(0)
	s_barrier
	s_setprio 1
	s_waitcnt lgkmcnt(0)
	v_mfma_f32_16x16x32_bf16 v[124:127], v[152:155], v[188:191], v[124:127]
	v_mfma_f32_16x16x32_bf16 v[124:127], v[156:159], v[192:195], v[124:127]
	v_mfma_f32_16x16x32_bf16 v[120:123], v[160:163], v[188:191], v[120:123]
	v_mfma_f32_16x16x32_bf16 v[120:123], v[164:167], v[192:195], v[120:123]
	v_mfma_f32_16x16x32_bf16 v[116:119], v[152:155], v[196:199], v[116:119]
	v_mfma_f32_16x16x32_bf16 v[116:119], v[156:159], v[200:203], v[116:119]
	v_mfma_f32_16x16x32_bf16 v[108:111], v[160:163], v[196:199], v[108:111]
	v_mfma_f32_16x16x32_bf16 v[108:111], v[164:167], v[200:203], v[108:111]
	v_mfma_f32_16x16x32_bf16 v[100:103], v[152:155], v[204:207], v[100:103]
	v_mfma_f32_16x16x32_bf16 v[100:103], v[156:159], v[208:211], v[100:103]
	v_mfma_f32_16x16x32_bf16 v[92:95], v[160:163], v[204:207], v[92:95]
	v_mfma_f32_16x16x32_bf16 v[92:95], v[164:167], v[208:211], v[92:95]
	v_mfma_f32_16x16x32_bf16 v[84:87], v[152:155], v[212:215], v[84:87]
	v_mfma_f32_16x16x32_bf16 v[84:87], v[156:159], v[216:219], v[84:87]
	v_mfma_f32_16x16x32_bf16 v[76:79], v[160:163], v[212:215], v[76:79]
	v_mfma_f32_16x16x32_bf16 v[76:79], v[164:167], v[216:219], v[76:79]
	v_mfma_f32_16x16x32_bf16 v[112:115], v[168:171], v[188:191], v[112:115]
	v_mfma_f32_16x16x32_bf16 v[112:115], v[172:175], v[192:195], v[112:115]
	v_mfma_f32_16x16x32_bf16 v[104:107], v[176:179], v[188:191], v[104:107]
	v_mfma_f32_16x16x32_bf16 v[104:107], v[184:187], v[192:195], v[104:107]
	v_mfma_f32_16x16x32_bf16 v[96:99], v[168:171], v[196:199], v[96:99]
	v_mfma_f32_16x16x32_bf16 v[96:99], v[172:175], v[200:203], v[96:99]
	v_mfma_f32_16x16x32_bf16 v[88:91], v[176:179], v[196:199], v[88:91]
	v_mfma_f32_16x16x32_bf16 v[88:91], v[184:187], v[200:203], v[88:91]
	v_mfma_f32_16x16x32_bf16 v[80:83], v[168:171], v[204:207], v[80:83]
	v_mfma_f32_16x16x32_bf16 v[80:83], v[172:175], v[208:211], v[80:83]
	v_mfma_f32_16x16x32_bf16 v[72:75], v[176:179], v[204:207], v[72:75]
	v_mfma_f32_16x16x32_bf16 v[72:75], v[184:187], v[208:211], v[72:75]
	v_mfma_f32_16x16x32_bf16 v[68:71], v[168:171], v[212:215], v[68:71]
	v_mfma_f32_16x16x32_bf16 v[68:71], v[172:175], v[216:219], v[68:71]
	v_mfma_f32_16x16x32_bf16 v[64:67], v[176:179], v[212:215], v[64:67]
	v_mfma_f32_16x16x32_bf16 v[64:67], v[184:187], v[216:219], v[64:67]
	s_setprio 0
	s_barrier
	s_add_i32 s46, s77, s56
	v_lshl_add_u64 v[144:145], v[144:145], 0, s[10:11]
	s_mov_b32 m0, s46
	ds_read_b128 v[188:191], v151 offset:49152
	ds_read_b128 v[192:195], v151 offset:50176
	ds_read_b128 v[196:199], v151 offset:51200
	ds_read_b128 v[200:203], v151 offset:52224
	ds_read_b128 v[204:207], v151 offset:53248
	ds_read_b128 v[208:211], v151 offset:54272
	ds_read_b128 v[212:215], v151 offset:55296
	ds_read_b128 v[216:219], v151 offset:56320
	global_load_lds_dwordx4 v[144:145], off
	s_add_i32 m0, s46, 0x2000
	s_add_u32 s46, s50, 0xb0080
	v_lshl_add_u64 v[144:145], v[220:221], 0, s[10:11]
	s_addc_u32 s47, s51, 0
	s_add_i32 s50, s79, s56
	global_load_lds_dwordx4 v[144:145], off
	v_lshl_add_u64 v[144:145], s[46:47], 0, v[130:131]
	s_mov_b32 m0, s50
	s_nop 0
	global_load_lds_dwordx4 v[144:145], off
	v_lshl_add_u64 v[144:145], s[46:47], 0, v[134:135]
	s_add_i32 m0, s50, 0x2000
	s_nop 0
	global_load_lds_dwordx4 v[144:145], off
	v_lshl_add_u64 v[144:145], v[222:223], 0, s[10:11]
	s_mov_b32 m0, s62
	s_nop 0
	global_load_lds_dwordx4 v[144:145], off nt
	v_lshl_add_u64 v[144:145], v[224:225], 0, s[10:11]
	s_mov_b32 m0, s63
	s_nop 0
	global_load_lds_dwordx4 v[144:145], off nt
	s_waitcnt vmcnt(8)
	s_waitcnt lgkmcnt(0)
	s_barrier
	s_setprio 1
	s_waitcnt lgkmcnt(0)
	v_mfma_f32_16x16x32_bf16 v[60:63], v[152:155], v[188:191], v[60:63]
	v_mfma_f32_16x16x32_bf16 v[60:63], v[156:159], v[192:195], v[60:63]
	v_mfma_f32_16x16x32_bf16 v[56:59], v[160:163], v[188:191], v[56:59]
	v_mfma_f32_16x16x32_bf16 v[56:59], v[164:167], v[192:195], v[56:59]
	v_mfma_f32_16x16x32_bf16 v[52:55], v[152:155], v[196:199], v[52:55]
	v_mfma_f32_16x16x32_bf16 v[52:55], v[156:159], v[200:203], v[52:55]
	v_mfma_f32_16x16x32_bf16 v[44:47], v[160:163], v[196:199], v[44:47]
	v_mfma_f32_16x16x32_bf16 v[44:47], v[164:167], v[200:203], v[44:47]
	v_mfma_f32_16x16x32_bf16 v[36:39], v[152:155], v[204:207], v[36:39]
	v_mfma_f32_16x16x32_bf16 v[36:39], v[156:159], v[208:211], v[36:39]
	v_mfma_f32_16x16x32_bf16 v[28:31], v[160:163], v[204:207], v[28:31]
	v_mfma_f32_16x16x32_bf16 v[28:31], v[164:167], v[208:211], v[28:31]
	v_mfma_f32_16x16x32_bf16 v[20:23], v[152:155], v[212:215], v[20:23]
	v_mfma_f32_16x16x32_bf16 v[20:23], v[156:159], v[216:219], v[20:23]
	v_mfma_f32_16x16x32_bf16 v[12:15], v[160:163], v[212:215], v[12:15]
	v_mfma_f32_16x16x32_bf16 v[12:15], v[164:167], v[216:219], v[12:15]
	v_mfma_f32_16x16x32_bf16 v[48:51], v[168:171], v[188:191], v[48:51]
	v_mfma_f32_16x16x32_bf16 v[48:51], v[172:175], v[192:195], v[48:51]
	v_mfma_f32_16x16x32_bf16 v[40:43], v[176:179], v[188:191], v[40:43]
	v_mfma_f32_16x16x32_bf16 v[40:43], v[184:187], v[192:195], v[40:43]
	v_mfma_f32_16x16x32_bf16 v[32:35], v[168:171], v[196:199], v[32:35]
	v_mfma_f32_16x16x32_bf16 v[32:35], v[172:175], v[200:203], v[32:35]
	v_mfma_f32_16x16x32_bf16 v[24:27], v[176:179], v[196:199], v[24:27]
	v_mfma_f32_16x16x32_bf16 v[24:27], v[184:187], v[200:203], v[24:27]
	v_mfma_f32_16x16x32_bf16 v[16:19], v[168:171], v[204:207], v[16:19]
	v_mfma_f32_16x16x32_bf16 v[16:19], v[172:175], v[208:211], v[16:19]
	v_mfma_f32_16x16x32_bf16 v[8:11], v[176:179], v[204:207], v[8:11]
	v_mfma_f32_16x16x32_bf16 v[8:11], v[184:187], v[208:211], v[8:11]
	v_mfma_f32_16x16x32_bf16 v[4:7], v[168:171], v[212:215], v[4:7]
	v_mfma_f32_16x16x32_bf16 v[4:7], v[172:175], v[216:219], v[4:7]
	v_mfma_f32_16x16x32_bf16 v[0:3], v[176:179], v[212:215], v[0:3]
	v_mfma_f32_16x16x32_bf16 v[0:3], v[184:187], v[216:219], v[0:3]
	s_setprio 0
	s_barrier
	s_add_i32 s76, s76, 2
	s_add_u32 s74, s74, 0x100
	s_addc_u32 s75, s75, 0
	s_cmp_gt_u32 s76, 41
	s_mov_b64 s[46:47], s[48:49]
	s_cbranch_scc0 .LBB0_1514
	s_and_b64 vcc, exec, s[12:13]
	s_cbranch_vccz .LBB0_1517
	s_barrier
